# tail spreading: leftover tiles of the last GEMM/merge round run on the first workgroup of distinct CUs; K/branch rotation keyed on the tile so outputs stay launch-invariant
# baseline (speedup 1.0000x reference)
.LBB0_134:
	s_andn2_b64 vcc, exec, s[2:3]
	s_movk_i32 s55, 0x4000
	v_readlane_b32 s54, v254, 59
	s_cbranch_vccnz .LBB0_165
	s_waitcnt vmcnt(0)
	v_mov_b32_e32 v74, v194
	s_movk_i32 s22, 0x1000
	s_movk_i32 s24, 0x1000
	s_movk_i32 s2, 0x1000
	v_lshlrev_b32_e32 v0, 3, v74
	v_ashrrev_i32_e32 v3, 3, v74
	v_and_b32_e32 v0, 56, v0
	v_lshrrev_b32_e32 v132, 4, v74
	v_xor_b32_e32 v132, v132, v74
	v_and_b32_e32 v132, 7, v132
	v_lshlrev_b32_e32 v0, 3, v132
	v_mov_b32_e32 v1, v2
	s_ashr_i32 s40, s2, 6
	s_ashr_i32 s41, s2, 9
	v_mad_i64_i32 v[4:5], s[2:3], s22, v3, v[0:1]
	v_mad_i64_i32 v[6:7], s[2:3], s24, v3, v[0:1]
	v_readlane_b32 s47, v254, 35
	s_mul_hi_i32 s3, s22, s47
	s_mul_i32 s2, s22, s47
	s_ashr_i32 s23, s22, 31
	s_ashr_i32 s25, s24, 31
	s_lshl_b64 s[2:3], s[2:3], 1
	s_add_u32 s2, s78, s2
	s_addc_u32 s3, s79, s3
	v_lshlrev_b64 v[68:69], 1, v[4:5]
	v_readlane_b32 s46, v254, 33
	v_lshl_add_u64 v[0:1], s[2:3], 0, v[68:69]
	s_mul_hi_i32 s3, s24, s46
	s_mul_i32 s2, s24, s46
	s_lshl_b64 s[26:27], s[2:3], 1
	s_add_u32 s2, s0, s26
	s_addc_u32 s3, s1, s27
	v_lshlrev_b64 v[70:71], 1, v[6:7]
	v_lshl_add_u64 v[138:139], s[2:3], 0, v[70:71]
	s_lshl_b64 s[2:3], s[22:23], 6
	s_waitcnt vmcnt(0)
	v_lshl_add_u64 v[28:29], v[0:1], 0, s[2:3]
	s_lshl_b64 s[20:21], s[24:25], 6
	s_waitcnt vmcnt(0)
	v_lshl_add_u64 v[36:37], v[28:29], 0, s[2:3]
	s_waitcnt vmcnt(0)
	v_lshl_add_u64 v[56:57], v[138:139], 0, s[20:21]
	v_lshl_add_u64 v[40:41], v[36:37], 0, s[2:3]
	s_waitcnt vmcnt(0)
	v_lshl_add_u64 v[60:61], v[56:57], 0, s[20:21]
	s_waitcnt vmcnt(0)
	v_lshl_add_u64 v[64:65], v[60:61], 0, s[20:21]
	s_bfe_u32 s100, s101, 0x20002
	s_lshl_b32 s100, s100, 10
	s_andn2_b32 s101, s101, 0x6000000
	s_add_u32 m0, s100, 0x0
	s_nop 0
	global_load_lds_dwordx4 v[0:1], off
	s_add_u32 m0, s100, 0x1000
	s_nop 0
	global_load_lds_dwordx4 v[28:29], off
	s_add_u32 m0, s100, 0x2000
	s_nop 0
	global_load_lds_dwordx4 v[36:37], off
	s_add_u32 m0, s100, 0x3000
	s_nop 0
	global_load_lds_dwordx4 v[40:41], off
	s_add_u32 m0, s100, 0x4000
	s_nop 0
	global_load_lds_dwordx4 v[138:139], off
	s_add_u32 m0, s100, 0x5000
	s_nop 0
	global_load_lds_dwordx4 v[56:57], off
	s_add_u32 m0, s100, 0x6000
	s_nop 0
	global_load_lds_dwordx4 v[60:61], off
	s_add_u32 m0, s100, 0x7000
	s_nop 0
	global_load_lds_dwordx4 v[64:65], off
	s_add_u32 m0, s100, 0x7f80
	s_nop 0
	global_load_lds_dwordx4 v[0:1], off offset:128
	s_add_u32 m0, s100, 0x8f80
	s_nop 0
	global_load_lds_dwordx4 v[28:29], off offset:128
	s_add_u32 m0, s100, 0x9f80
	s_nop 0
	global_load_lds_dwordx4 v[36:37], off offset:128
	s_add_u32 m0, s100, 0xaf80
	s_nop 0
	global_load_lds_dwordx4 v[40:41], off offset:128
	s_add_u32 m0, s100, 0xbf80
	s_nop 0
	global_load_lds_dwordx4 v[138:139], off offset:128
	s_add_u32 m0, s100, 0xcf80
	s_nop 0
	global_load_lds_dwordx4 v[56:57], off offset:128
	s_add_u32 m0, s100, 0xdf80
	s_nop 0
	global_load_lds_dwordx4 v[60:61], off offset:128
	s_add_u32 m0, s100, 0xef80
	s_nop 0
	global_load_lds_dwordx4 v[64:65], off offset:128
	v_lshlrev_b32_e32 v72, 7, v3
	v_lshrrev_b32_e32 v3, 1, v3
	v_xor_b32_e32 v3, v3, v74
	v_lshl_add_u64 v[70:71], s[0:1], 0, v[70:71]
	v_readlane_b32 s0, v254, 34
	v_lshlrev_b32_e32 v3, 4, v3
	s_movk_i32 s6, 0x70
	v_lshl_add_u64 v[68:69], s[78:79], 0, v[68:69]
	s_mul_hi_i32 s1, s22, s0
	s_mul_i32 s0, s22, s0
	v_and_or_b32 v3, v3, s6, v72
	v_lshl_add_u64 v[72:73], s[0:1], 1, v[68:69]
	v_readlane_b32 s0, v254, 31
	s_mul_hi_i32 s1, s41, s0
	s_mul_i32 s0, s41, s0
	v_readlane_b32 s6, v254, 32
	s_lshl_b64 s[0:1], s[0:1], 1
	s_mul_hi_i32 s25, s24, s6
	s_mul_i32 s24, s24, s6
	v_lshl_add_u64 v[140:141], v[72:73], 0, s[0:1]
	v_lshl_add_u64 v[72:73], s[24:25], 1, v[70:71]
	v_lshl_add_u64 v[142:143], v[72:73], 0, s[0:1]
	s_mul_hi_i32 s1, s22, s54
	s_mul_i32 s0, s22, s54
	v_lshrrev_b32_e32 v75, 4, v74
	v_bfe_u32 v76, v74, 4, 2
	v_lshl_add_u64 v[144:145], s[0:1], 1, v[68:69]
	v_bfe_u32 v68, v74, 1, 3
	v_lshl_add_u64 v[146:147], v[70:71], 0, s[26:27]
	v_bitop3_b32 v69, v75, v68, 3 bitop3:0x6c
	v_lshlrev_b32_e32 v70, 6, v74
	v_lshlrev_b32_e32 v71, 7, v74
	v_bitop3_b32 v68, v76, v68, 4 bitop3:0x36
	v_lshlrev_b32_e32 v69, 4, v69
	v_and_b32_e32 v70, 0xffffe000, v70
	v_and_b32_e32 v72, 0x780, v71
	v_and_b32_e32 v71, 0x2000, v71
	v_lshlrev_b32_e32 v68, 4, v68
	v_or_b32_e32 v73, v69, v70
	v_or_b32_e32 v69, v69, v71
	v_or_b32_e32 v70, v68, v70
	v_or_b32_e32 v68, v68, v71
	s_mov_b32 s42, 0
	v_add_u32_e32 v137, v73, v72
	v_add_u32_e32 v192, v69, v72
	v_add_u32_e32 v193, v70, v72
	v_add_u32_e32 v214, v68, v72
	s_mov_b32 s43, s40
	s_mov_b32 s44, 0
	s_mov_b32 s45, 0
	s_bfe_u32 vcc_lo, s101, 0x10001
	v_and_b32_e32 v20, 15, v194
	v_lshrrev_b32_e32 v21, 1, v20
	v_bfe_u32 v22, v194, 4, 2
	v_xor_b32_e32 v21, v21, v22
	v_lshlrev_b32_e32 v21, 4, v21
	v_lshl_or_b32 v250, v20, 7, v21
	v_mov_b32_e32 v22, vcc_lo
	v_lshl_or_b32 v22, v22, 13, v250
	v_or_b32_e32 v251, 0x4000, v22
	v_and_b32_e32 v20, 63, v194
	v_mov_b32_e32 v21, vcc_lo
	v_lshlrev_b32_e32 v21, 4, v21
	v_lshrrev_b32_e32 v22, 3, v20
	v_add_u32_e32 v21, v21, v22
	v_lshrrev_b32_e32 v22, 4, v20
	v_and_b32_e32 v23, 7, v20
	v_xor_b32_e32 v24, v23, v22
	v_lshlrev_b32_e32 v24, 4, v24
	v_or_b32_e32 v22, 4, v22
	v_xor_b32_e32 v25, v23, v22
	v_lshlrev_b32_e32 v25, 4, v25
	s_movk_i32 s98, 0x2000
	s_movk_i32 s99, 0x2000
	v_add_u32_e32 v26, 0, v21
	v_mad_u32_u24 v4, v26, s98, v24
	v_add_u32_e32 v26, 8, v21
	v_mad_u32_u24 v5, v26, s98, v25
	v_add_u32_e32 v26, 32, v21
	v_mad_u32_u24 v6, v26, s98, v24
	v_add_u32_e32 v26, 40, v21
	v_mad_u32_u24 v7, v26, s98, v25
	v_add_u32_e32 v26, 64, v21
	v_mad_u32_u24 v8, v26, s98, v24
	v_add_u32_e32 v26, 72, v21
	v_mad_u32_u24 v9, v26, s98, v25
	v_add_u32_e32 v26, 96, v21
	v_mad_u32_u24 v10, v26, s98, v24
	v_add_u32_e32 v26, 104, v21
	v_mad_u32_u24 v11, v26, s98, v25
	v_add_u32_e32 v26, 0, v21
	v_mad_u32_u24 v12, v26, s99, v24
	v_add_u32_e32 v26, 8, v21
	v_mad_u32_u24 v13, v26, s99, v25
	v_add_u32_e32 v26, 32, v21
	v_mad_u32_u24 v14, v26, s99, v24
	v_add_u32_e32 v26, 40, v21
	v_mad_u32_u24 v15, v26, s99, v25
	v_add_u32_e32 v26, 64, v21
	v_mad_u32_u24 v16, v26, s99, v24
	v_add_u32_e32 v26, 72, v21
	v_mad_u32_u24 v17, v26, s99, v25
	v_add_u32_e32 v26, 96, v21
	v_mad_u32_u24 v18, v26, s99, v24
	v_add_u32_e32 v26, 104, v21
	v_mad_u32_u24 v19, v26, s99, v25
	s_bfe_u32 vcc_hi, s101, 0x20002
	s_lshl_b32 vcc_hi, vcc_hi, 3
	s_mul_i32 s98, s98, vcc_hi
	s_mul_i32 s99, s99, vcc_hi
	s_lshl_b32 vcc_hi, vcc_hi, 3
	s_and_b32 vcc_hi, vcc_hi, 0x70
	s_add_u32 s98, s98, vcc_hi
	s_add_u32 s99, s99, vcc_hi
	s_lshl_b32 s100, vcc_lo, 11
	s_bitcmp1_b32 s101, 0
	s_cselect_b32 s100, -1, s100
	s_waitcnt vmcnt(0) lgkmcnt(0)
	s_barrier
	s_branch .LBB0_138

.LBB0_166:
	s_andn2_b64 vcc, exec, s[0:1]
	s_cbranch_vccnz .LBB0_191
	v_readlane_b32 s6, v253, 13
	s_waitcnt vmcnt(1)
	v_mov_b32_e32 v68, v194
	s_movk_i32 s0, 0x400
	s_movk_i32 s2, 0x400
	s_movk_i32 s3, 0x400
	v_readlane_b32 s7, v253, 14
	s_load_dword s1, s[6:7], 0x0
	v_readlane_b32 s6, v254, 30
	s_waitcnt lgkmcnt(0)
	s_lshr_b32 s46, s1, 3
	v_readlane_b32 s1, v254, 36
	s_mul_i32 s1, s46, s1
	s_add_i32 s1, s1, s6
	s_cmpk_gt_i32 s1, 0x10ff
	s_cbranch_scc1 .LBB0_191
	s_ashr_i32 s47, s3, 6
	s_lshl_b32 s3, s8, 1
	v_readlane_b32 s8, v252, 37
	v_readlane_b32 s18, v252, 47
	v_readlane_b32 s19, v252, 48
	s_add_u32 s24, s18, s3
	s_addc_u32 s25, s19, 0
	s_ashr_i32 s3, s1, 31
	s_lshr_b32 s3, s3, 24
	v_readlane_b32 s21, v252, 50
	s_add_i32 s3, s1, s3
	v_readlane_b32 s20, v252, 49
	s_ashr_i32 s3, s3, 8
	s_lshl_b32 s21, s1, 7
	v_lshlrev_b32_e32 v0, 3, v68
	v_ashrrev_i32_e32 v3, 3, v68
	s_lshl_b32 s20, s3, 10
	s_and_b32 s21, s21, 0x380
	v_and_b32_e32 v0, 56, v0
	v_lshrrev_b32_e32 v132, 4, v68
	v_xor_b32_e32 v132, v132, v68
	v_and_b32_e32 v132, 7, v132
	v_lshlrev_b32_e32 v0, 3, v132
	v_mov_b32_e32 v1, v2
	s_or_b32 s53, s20, s21
	s_lshl_b32 s3, s3, 12
	s_lshl_b32 s1, s1, 4
	v_mad_i64_i32 v[4:5], s[20:21], s0, v3, v[0:1]
	v_mad_i64_i32 v[0:1], s[20:21], s2, v3, v[0:1]
	s_sub_i32 s1, s1, s3
	s_mul_hi_i32 s21, s53, s0
	s_mul_i32 s20, s53, s0
	s_and_b32 s52, s1, 0xffffff80
	s_ashr_i32 s1, s0, 31
	s_ashr_i32 s3, s2, 31
	s_lshl_b64 s[20:21], s[20:21], 1
	s_add_u32 s20, s76, s20
	s_addc_u32 s21, s77, s21
	v_lshlrev_b64 v[70:71], 1, v[4:5]
	v_lshl_add_u64 v[144:145], s[20:21], 0, v[70:71]
	s_mul_hi_i32 s21, s52, s2
	s_mul_i32 s20, s52, s2
	s_lshl_b64 s[20:21], s[20:21], 1
	s_add_u32 s20, s24, s20
	s_addc_u32 s21, s25, s21
	s_waitcnt vmcnt(0)
	v_lshlrev_b64 v[72:73], 1, v[0:1]
	v_readlane_b32 s22, v252, 51
	v_readlane_b32 s23, v252, 52
	v_lshl_add_u64 v[146:147], s[20:21], 0, v[72:73]
	s_lshl_b64 s[20:21], s[0:1], 6
	v_lshl_add_u64 v[0:1], v[144:145], 0, s[20:21]
	s_lshl_b64 s[22:23], s[2:3], 6
	s_waitcnt vmcnt(0)
	v_lshl_add_u64 v[36:37], v[0:1], 0, s[20:21]
	s_waitcnt vmcnt(0)
	v_lshl_add_u64 v[56:57], v[146:147], 0, s[22:23]
	v_lshl_add_u64 v[40:41], v[36:37], 0, s[20:21]
	s_waitcnt vmcnt(0)
	v_lshl_add_u64 v[60:61], v[56:57], 0, s[22:23]
	s_waitcnt vmcnt(0)
	v_lshl_add_u64 v[64:65], v[60:61], 0, s[22:23]
	s_bfe_u32 s100, s101, 0x20002
	s_lshl_b32 s100, s100, 10
	s_andn2_b32 s101, s101, 0x6000000
	s_bfe_u32 vcc_lo, s101, 0x80008
	s_add_u32 vcc_lo, vcc_lo, 0
	s_add_u32 vcc_hi, s47, -1
	s_and_b32 vcc_lo, vcc_lo, vcc_hi
	s_lshl_b32 vcc_lo, vcc_lo, 7
	s_mov_b32 vcc_hi, 0
	v_lshl_add_u64 v[20:21], v[144:145], 0, vcc
	s_add_u32 m0, s100, 0x0
	s_nop 0
	global_load_lds_dwordx4 v[20:21], off
	v_lshl_add_u64 v[20:21], v[0:1], 0, vcc
	s_add_u32 m0, s100, 0x1000
	s_nop 0
	global_load_lds_dwordx4 v[20:21], off
	v_lshl_add_u64 v[20:21], v[36:37], 0, vcc
	s_add_u32 m0, s100, 0x2000
	s_nop 0
	global_load_lds_dwordx4 v[20:21], off
	v_lshl_add_u64 v[20:21], v[40:41], 0, vcc
	s_add_u32 m0, s100, 0x3000
	s_nop 0
	global_load_lds_dwordx4 v[20:21], off
	v_lshl_add_u64 v[20:21], v[146:147], 0, vcc
	s_add_u32 m0, s100, 0x4000
	s_nop 0
	global_load_lds_dwordx4 v[20:21], off
	v_lshl_add_u64 v[20:21], v[56:57], 0, vcc
	s_add_u32 m0, s100, 0x5000
	s_nop 0
	global_load_lds_dwordx4 v[20:21], off
	v_lshl_add_u64 v[20:21], v[60:61], 0, vcc
	s_add_u32 m0, s100, 0x6000
	s_nop 0
	global_load_lds_dwordx4 v[20:21], off
	v_lshl_add_u64 v[20:21], v[64:65], 0, vcc
	s_add_u32 m0, s100, 0x7000
	s_nop 0
	global_load_lds_dwordx4 v[20:21], off
	s_bfe_u32 vcc_lo, s101, 0x80008
	s_add_u32 vcc_lo, vcc_lo, 1
	s_add_u32 vcc_hi, s47, -1
	s_and_b32 vcc_lo, vcc_lo, vcc_hi
	s_lshl_b32 vcc_lo, vcc_lo, 7
	s_mov_b32 vcc_hi, 0
	v_lshl_add_u64 v[20:21], v[144:145], 0, vcc
	s_add_u32 m0, s100, 0x8000
	s_nop 0
	global_load_lds_dwordx4 v[20:21], off
	v_lshl_add_u64 v[20:21], v[0:1], 0, vcc
	s_add_u32 m0, s100, 0x9000
	s_nop 0
	global_load_lds_dwordx4 v[20:21], off
	v_lshl_add_u64 v[20:21], v[36:37], 0, vcc
	s_add_u32 m0, s100, 0xa000
	s_nop 0
	global_load_lds_dwordx4 v[20:21], off
	v_lshl_add_u64 v[20:21], v[40:41], 0, vcc
	s_add_u32 m0, s100, 0xb000
	s_nop 0
	global_load_lds_dwordx4 v[20:21], off
	v_lshl_add_u64 v[20:21], v[146:147], 0, vcc
	s_add_u32 m0, s100, 0xc000
	s_nop 0
	global_load_lds_dwordx4 v[20:21], off
	v_lshl_add_u64 v[20:21], v[56:57], 0, vcc
	s_add_u32 m0, s100, 0xd000
	s_nop 0
	global_load_lds_dwordx4 v[20:21], off
	v_lshl_add_u64 v[20:21], v[60:61], 0, vcc
	s_add_u32 m0, s100, 0xe000
	s_nop 0
	global_load_lds_dwordx4 v[20:21], off
	v_lshl_add_u64 v[20:21], v[64:65], 0, vcc
	s_add_u32 m0, s100, 0xf000
	s_nop 0
	global_load_lds_dwordx4 v[20:21], off
	v_lshrrev_b32_e32 v1, 1, v3
	v_xor_b32_e32 v1, v1, v68
	v_lshlrev_b32_e32 v0, 7, v3
	v_lshlrev_b32_e32 v1, 4, v1
	s_movk_i32 s1, 0x70
	v_lshrrev_b32_e32 v69, 4, v68
	v_bfe_u32 v74, v68, 4, 2
	v_and_or_b32 v3, v1, s1, v0
	v_lshl_add_u64 v[0:1], s[76:77], 0, v[70:71]
	v_bfe_u32 v70, v68, 1, 3
	v_bitop3_b32 v69, v69, v70, 3 bitop3:0x6c
	v_lshlrev_b32_e32 v71, 6, v68
	v_lshlrev_b32_e32 v68, 7, v68
	v_bitop3_b32 v70, v74, v70, 4 bitop3:0x36
	v_lshl_add_u64 v[138:139], s[24:25], 0, v[72:73]
	v_lshlrev_b32_e32 v69, 4, v69
	v_and_b32_e32 v71, 0xffffe000, v71
	v_and_b32_e32 v72, 0x780, v68
	v_and_b32_e32 v68, 0x2000, v68
	v_lshlrev_b32_e32 v70, 4, v70
	s_cmp_gt_i32 s47, 0
	v_or_b32_e32 v73, v69, v71
	v_or_b32_e32 v69, v69, v68
	v_or_b32_e32 v71, v70, v71
	v_or_b32_e32 v68, v70, v68
	s_mov_b32 s1, 0
	s_cselect_b64 s[24:25], -1, 0
	v_add_u32_e32 v137, v73, v72
	v_add_u32_e32 v188, v69, v72
	v_add_u32_e32 v189, v71, v72
	v_add_u32_e32 v190, v68, v72
	s_mov_b32 s3, 0
	s_mov_b32 s49, 0
	v_readlane_b32 s9, v252, 38
	v_readlane_b32 s10, v252, 39
	v_readlane_b32 s11, v252, 40
	v_readlane_b32 s12, v252, 41
	v_readlane_b32 s13, v252, 42
	v_readlane_b32 s14, v252, 43
	v_readlane_b32 s15, v252, 44
	v_readlane_b32 s16, v252, 45
	v_readlane_b32 s17, v252, 46
	s_bfe_u32 vcc_lo, s101, 0x10001
	v_and_b32_e32 v20, 15, v194
	v_lshrrev_b32_e32 v21, 1, v20
	v_bfe_u32 v22, v194, 4, 2
	v_xor_b32_e32 v21, v21, v22
	v_lshlrev_b32_e32 v21, 4, v21
	v_lshl_or_b32 v250, v20, 7, v21
	v_mov_b32_e32 v22, vcc_lo
	v_lshl_or_b32 v22, v22, 13, v250
	v_or_b32_e32 v251, 0x4000, v22
	v_and_b32_e32 v20, 63, v194
	v_mov_b32_e32 v21, vcc_lo
	v_lshlrev_b32_e32 v21, 4, v21
	v_lshrrev_b32_e32 v22, 3, v20
	v_add_u32_e32 v21, v21, v22
	v_lshrrev_b32_e32 v22, 4, v20
	v_and_b32_e32 v23, 7, v20
	v_xor_b32_e32 v24, v23, v22
	v_lshlrev_b32_e32 v24, 4, v24
	v_or_b32_e32 v22, 4, v22
	v_xor_b32_e32 v25, v23, v22
	v_lshlrev_b32_e32 v25, 4, v25
	s_movk_i32 s98, 0x800
	s_movk_i32 s99, 0x800
	v_add_u32_e32 v26, 0, v21
	v_mad_u32_u24 v4, v26, s98, v24
	v_add_u32_e32 v26, 8, v21
	v_mad_u32_u24 v5, v26, s98, v25
	v_add_u32_e32 v26, 32, v21
	v_mad_u32_u24 v6, v26, s98, v24
	v_add_u32_e32 v26, 40, v21
	v_mad_u32_u24 v7, v26, s98, v25
	v_add_u32_e32 v26, 64, v21
	v_mad_u32_u24 v8, v26, s98, v24
	v_add_u32_e32 v26, 72, v21
	v_mad_u32_u24 v9, v26, s98, v25
	v_add_u32_e32 v26, 96, v21
	v_mad_u32_u24 v10, v26, s98, v24
	v_add_u32_e32 v26, 104, v21
	v_mad_u32_u24 v11, v26, s98, v25
	v_add_u32_e32 v26, 0, v21
	v_mad_u32_u24 v12, v26, s99, v24
	v_add_u32_e32 v26, 8, v21
	v_mad_u32_u24 v13, v26, s99, v25
	v_add_u32_e32 v26, 32, v21
	v_mad_u32_u24 v14, v26, s99, v24
	v_add_u32_e32 v26, 40, v21
	v_mad_u32_u24 v15, v26, s99, v25
	v_add_u32_e32 v26, 64, v21
	v_mad_u32_u24 v16, v26, s99, v24
	v_add_u32_e32 v26, 72, v21
	v_mad_u32_u24 v17, v26, s99, v25
	v_add_u32_e32 v26, 96, v21
	v_mad_u32_u24 v18, v26, s99, v24
	v_add_u32_e32 v26, 104, v21
	v_mad_u32_u24 v19, v26, s99, v25
	s_bfe_u32 vcc_hi, s101, 0x20002
	s_lshl_b32 vcc_hi, vcc_hi, 3
	s_mul_i32 s98, s98, vcc_hi
	s_mul_i32 s99, s99, vcc_hi
	s_lshl_b32 vcc_hi, vcc_hi, 3
	s_and_b32 vcc_hi, vcc_hi, 0x70
	s_add_u32 s98, s98, vcc_hi
	s_add_u32 s99, s99, vcc_hi
	s_lshl_b32 s100, vcc_lo, 11
	s_bitcmp1_b32 s101, 0
	s_cselect_b32 s100, -1, s100
	s_waitcnt vmcnt(0) lgkmcnt(0)
	s_barrier
	s_branch .LBB0_171

.LBB0_171:
	s_add_i32 s49, s49, 1
	s_lshl_b32 s26, s49, 3
	v_readlane_b32 s6, v254, 36
	s_or_b32 s26, s26, s6
	s_mul_i32 s34, s26, s46
	v_readlane_b32 s6, v254, 30
	s_add_i32 s34, s34, s6
	s_sub_u32 s26, s34, 0x1000
	s_cmp_lt_u32 s26, 0x200
	s_cbranch_scc0 .Ltailfix_0
	s_bfe_u32 s34, s101, 0x80010
	s_add_u32 s34, s34, 0x1000
	s_bitcmp1_b32 s101, 24
	s_cselect_b32 s34, s34, 0x7fff
	s_or_b32 s101, s101, 0x2000000

.Lpc_pgo_2:
	s_nop 0
	s_sub_u32 s40, s40, s98
	s_subb_u32 s41, s41, 0
	s_sub_u32 s38, s38, s99
	s_subb_u32 s39, s39, 0
	s_bfe_u32 vcc_hi, s101, 0x80008
	s_cmp_lt_i32 s55, s47
	s_cselect_b32 m0, 26, 25
	s_bitcmp1_b32 s101, m0
	s_cbranch_scc0 .Lpc_rt_2_0
	s_bfe_u32 vcc_hi, s101, 0x80010
.Lpc_rt_2_0:
	s_add_u32 vcc_hi, vcc_hi, vcc_lo
	s_add_u32 m0, s42, -1
	s_and_b32 vcc_hi, vcc_hi, m0
	s_lshl_b32 vcc_hi, vcc_hi, 7
	v_add_u32_e32 v20, vcc_hi, v4
	v_add_u32_e32 v21, vcc_hi, v5
	v_add_u32_e32 v22, vcc_hi, v6
	v_add_u32_e32 v23, vcc_hi, v7
	v_add_u32_e32 v24, vcc_hi, v8
	v_add_u32_e32 v25, vcc_hi, v9
	v_add_u32_e32 v26, vcc_hi, v10
	v_add_u32_e32 v27, vcc_hi, v11
	v_add_u32_e32 v28, vcc_hi, v12
	v_add_u32_e32 v29, vcc_hi, v13
	v_add_u32_e32 v30, vcc_hi, v14
	v_add_u32_e32 v31, vcc_hi, v15
	v_add_u32_e32 v32, vcc_hi, v16
	v_add_u32_e32 v33, vcc_hi, v17
	v_add_u32_e32 v34, vcc_hi, v18
	v_add_u32_e32 v35, vcc_hi, v19
	s_add_u32 vcc_lo, vcc_lo, 1
	s_barrier
	s_add_u32 m0, s100, 0x0
	s_nop 0
	global_load_lds_dwordx4 v20, s[40:41]
	s_add_u32 m0, s100, 0x400
	s_nop 0
	global_load_lds_dwordx4 v21, s[40:41]
	s_add_u32 m0, s100, 0x1000
	s_nop 0
	global_load_lds_dwordx4 v22, s[40:41]
	s_add_u32 m0, s100, 0x1400
	s_nop 0
	global_load_lds_dwordx4 v23, s[40:41]
	s_add_u32 m0, s100, 0x2000
	s_nop 0
	global_load_lds_dwordx4 v24, s[40:41]
	s_add_u32 m0, s100, 0x2400
	s_nop 0
	global_load_lds_dwordx4 v25, s[40:41]
	s_add_u32 m0, s100, 0x3000
	s_nop 0
	global_load_lds_dwordx4 v26, s[40:41]
	s_add_u32 m0, s100, 0x3400
	s_nop 0
	global_load_lds_dwordx4 v27, s[40:41]
	s_waitcnt vmcnt(8)
	s_barrier
	s_add_u32 m0, s100, 0x4000
	s_nop 0
	global_load_lds_dwordx4 v28, s[38:39]
	s_add_u32 m0, s100, 0x4400
	s_nop 0
	global_load_lds_dwordx4 v29, s[38:39]
	s_add_u32 m0, s100, 0x5000
	s_nop 0
	global_load_lds_dwordx4 v30, s[38:39]
	s_add_u32 m0, s100, 0x5400
	s_nop 0
	global_load_lds_dwordx4 v31, s[38:39]
	s_add_u32 m0, s100, 0x6000
	s_nop 0
	global_load_lds_dwordx4 v32, s[38:39]
	s_add_u32 m0, s100, 0x6400
	s_nop 0
	global_load_lds_dwordx4 v33, s[38:39]
	s_add_u32 m0, s100, 0x7000
	s_nop 0
	global_load_lds_dwordx4 v34, s[38:39]
	s_add_u32 m0, s100, 0x7400
	s_nop 0
	global_load_lds_dwordx4 v35, s[38:39]
	s_bfe_u32 vcc_hi, s101, 0x80008
	s_cmp_lt_i32 s55, s47
	s_cselect_b32 m0, 26, 25
	s_bitcmp1_b32 s101, m0
	s_cbranch_scc0 .Lpc_rt_2_1
	s_bfe_u32 vcc_hi, s101, 0x80010
.Lpc_rt_2_1:
	s_add_u32 vcc_hi, vcc_hi, vcc_lo
	s_add_u32 m0, s42, -1
	s_and_b32 vcc_hi, vcc_hi, m0
	s_lshl_b32 vcc_hi, vcc_hi, 7
	v_add_u32_e32 v20, vcc_hi, v4
	v_add_u32_e32 v21, vcc_hi, v5
	v_add_u32_e32 v22, vcc_hi, v6
	v_add_u32_e32 v23, vcc_hi, v7
	v_add_u32_e32 v24, vcc_hi, v8
	v_add_u32_e32 v25, vcc_hi, v9
	v_add_u32_e32 v26, vcc_hi, v10
	v_add_u32_e32 v27, vcc_hi, v11
	v_add_u32_e32 v28, vcc_hi, v12
	v_add_u32_e32 v29, vcc_hi, v13
	v_add_u32_e32 v30, vcc_hi, v14
	v_add_u32_e32 v31, vcc_hi, v15
	v_add_u32_e32 v32, vcc_hi, v16
	v_add_u32_e32 v33, vcc_hi, v17
	v_add_u32_e32 v34, vcc_hi, v18
	v_add_u32_e32 v35, vcc_hi, v19
	s_add_u32 vcc_lo, vcc_lo, 1
	s_barrier
	s_add_u32 m0, s100, 0x8000
	s_nop 0
	global_load_lds_dwordx4 v20, s[40:41]
	s_add_u32 m0, s100, 0x8400
	s_nop 0
	global_load_lds_dwordx4 v21, s[40:41]
	s_add_u32 m0, s100, 0x9000
	s_nop 0
	global_load_lds_dwordx4 v22, s[40:41]
	s_add_u32 m0, s100, 0x9400
	s_nop 0
	global_load_lds_dwordx4 v23, s[40:41]
	s_add_u32 m0, s100, 0xa000
	s_nop 0
	global_load_lds_dwordx4 v24, s[40:41]
	s_add_u32 m0, s100, 0xa400
	s_nop 0
	global_load_lds_dwordx4 v25, s[40:41]
	s_add_u32 m0, s100, 0xb000
	s_nop 0
	global_load_lds_dwordx4 v26, s[40:41]
	s_add_u32 m0, s100, 0xb400
	s_nop 0
	global_load_lds_dwordx4 v27, s[40:41]
	s_waitcnt vmcnt(8)
	s_barrier
	s_add_u32 m0, s100, 0xc000
	s_nop 0
	global_load_lds_dwordx4 v28, s[38:39]
	s_add_u32 m0, s100, 0xc400
	s_nop 0
	global_load_lds_dwordx4 v29, s[38:39]
	s_add_u32 m0, s100, 0xd000
	s_nop 0
	global_load_lds_dwordx4 v30, s[38:39]
	s_add_u32 m0, s100, 0xd400
	s_nop 0
	global_load_lds_dwordx4 v31, s[38:39]
	s_add_u32 m0, s100, 0xe000
	s_nop 0
	global_load_lds_dwordx4 v32, s[38:39]
	s_add_u32 m0, s100, 0xe400
	s_nop 0
	global_load_lds_dwordx4 v33, s[38:39]
	s_add_u32 m0, s100, 0xf000
	s_nop 0
	global_load_lds_dwordx4 v34, s[38:39]
	s_add_u32 m0, s100, 0xf400
	s_nop 0
	global_load_lds_dwordx4 v35, s[38:39]
	s_add_u32 s34, s34, 0x100
	s_addc_u32 s35, s35, 0
	s_add_i32 s55, s55, 2
	s_cmp_le_i32 s55, s47
	s_cbranch_scc1 .Lpc_ptop_2
	s_setprio 0
	s_bfe_u32 m0, s101, 0x10019
	s_andn2_b32 s101, s101, 0x6000000
	s_lshl_b32 m0, m0, 26
	s_or_b32 s101, s101, m0
	s_movk_i32 s55, 0x4000
	s_mov_b32 s53, s1
	s_mov_b32 s52, s3
	s_and_b64 vcc, exec, s[26:27]
	v_mov_b64_e32 v[146:147], v[142:143]
	v_mov_b64_e32 v[144:145], v[140:141]
	s_cbranch_vccz .Lpc_pnd_2
	s_waitcnt vmcnt(0)
	s_branch .LBB0_191

.LBB0_245:
	s_andn2_b64 vcc, exec, s[2:3]
	s_cbranch_vccnz .LBB0_276
	s_waitcnt vmcnt(0)
	v_mov_b32_e32 v74, v194
	s_movk_i32 s22, 0x400
	s_movk_i32 s24, 0x400
	s_movk_i32 s2, 0x400
	v_lshlrev_b32_e32 v0, 3, v74
	v_ashrrev_i32_e32 v3, 3, v74
	v_and_b32_e32 v0, 56, v0
	v_lshrrev_b32_e32 v132, 4, v74
	v_xor_b32_e32 v132, v132, v74
	v_and_b32_e32 v132, 7, v132
	v_lshlrev_b32_e32 v0, 3, v132
	v_mov_b32_e32 v1, v2
	s_ashr_i32 s40, s2, 6
	s_ashr_i32 s41, s2, 9
	v_mad_i64_i32 v[4:5], s[2:3], s22, v3, v[0:1]
	v_mad_i64_i32 v[6:7], s[2:3], s24, v3, v[0:1]
	v_readlane_b32 s47, v254, 35
	s_mul_hi_i32 s3, s22, s47
	s_mul_i32 s2, s22, s47
	s_ashr_i32 s23, s22, 31
	s_ashr_i32 s25, s24, 31
	s_lshl_b64 s[2:3], s[2:3], 1
	s_add_u32 s2, s76, s2
	s_addc_u32 s3, s77, s3
	v_lshlrev_b64 v[68:69], 1, v[4:5]
	v_readlane_b32 s46, v254, 33
	v_lshl_add_u64 v[0:1], s[2:3], 0, v[68:69]
	s_mul_hi_i32 s3, s24, s46
	s_mul_i32 s2, s24, s46
	s_lshl_b64 s[26:27], s[2:3], 1
	s_add_u32 s2, s0, s26
	s_addc_u32 s3, s1, s27
	v_lshlrev_b64 v[70:71], 1, v[6:7]
	v_lshl_add_u64 v[138:139], s[2:3], 0, v[70:71]
	s_lshl_b64 s[2:3], s[22:23], 6
	s_waitcnt vmcnt(0)
	v_lshl_add_u64 v[28:29], v[0:1], 0, s[2:3]
	s_lshl_b64 s[20:21], s[24:25], 6
	s_waitcnt vmcnt(0)
	v_lshl_add_u64 v[36:37], v[28:29], 0, s[2:3]
	s_waitcnt vmcnt(0)
	v_lshl_add_u64 v[56:57], v[138:139], 0, s[20:21]
	v_lshl_add_u64 v[40:41], v[36:37], 0, s[2:3]
	s_waitcnt vmcnt(0)
	v_lshl_add_u64 v[60:61], v[56:57], 0, s[20:21]
	s_waitcnt vmcnt(0)
	v_lshl_add_u64 v[64:65], v[60:61], 0, s[20:21]
	s_bfe_u32 s100, s101, 0x20002
	s_lshl_b32 s100, s100, 10
	s_andn2_b32 s101, s101, 0x6000000
	s_add_u32 m0, s100, 0x0
	s_nop 0
	global_load_lds_dwordx4 v[0:1], off
	s_add_u32 m0, s100, 0x1000
	s_nop 0
	global_load_lds_dwordx4 v[28:29], off
	s_add_u32 m0, s100, 0x2000
	s_nop 0
	global_load_lds_dwordx4 v[36:37], off
	s_add_u32 m0, s100, 0x3000
	s_nop 0
	global_load_lds_dwordx4 v[40:41], off
	s_add_u32 m0, s100, 0x4000
	s_nop 0
	global_load_lds_dwordx4 v[138:139], off
	s_add_u32 m0, s100, 0x5000
	s_nop 0
	global_load_lds_dwordx4 v[56:57], off
	s_add_u32 m0, s100, 0x6000
	s_nop 0
	global_load_lds_dwordx4 v[60:61], off
	s_add_u32 m0, s100, 0x7000
	s_nop 0
	global_load_lds_dwordx4 v[64:65], off
	s_add_u32 m0, s100, 0x7f80
	s_nop 0
	global_load_lds_dwordx4 v[0:1], off offset:128
	s_add_u32 m0, s100, 0x8f80
	s_nop 0
	global_load_lds_dwordx4 v[28:29], off offset:128
	s_add_u32 m0, s100, 0x9f80
	s_nop 0
	global_load_lds_dwordx4 v[36:37], off offset:128
	s_add_u32 m0, s100, 0xaf80
	s_nop 0
	global_load_lds_dwordx4 v[40:41], off offset:128
	s_add_u32 m0, s100, 0xbf80
	s_nop 0
	global_load_lds_dwordx4 v[138:139], off offset:128
	s_add_u32 m0, s100, 0xcf80
	s_nop 0
	global_load_lds_dwordx4 v[56:57], off offset:128
	s_add_u32 m0, s100, 0xdf80
	s_nop 0
	global_load_lds_dwordx4 v[60:61], off offset:128
	s_add_u32 m0, s100, 0xef80
	s_nop 0
	global_load_lds_dwordx4 v[64:65], off offset:128
	v_lshlrev_b32_e32 v72, 7, v3
	v_lshrrev_b32_e32 v3, 1, v3
	v_xor_b32_e32 v3, v3, v74
	v_lshl_add_u64 v[70:71], s[0:1], 0, v[70:71]
	v_readlane_b32 s0, v254, 34
	v_lshlrev_b32_e32 v3, 4, v3
	s_movk_i32 s6, 0x70
	v_lshl_add_u64 v[68:69], s[76:77], 0, v[68:69]
	s_mul_hi_i32 s1, s22, s0
	s_mul_i32 s0, s22, s0
	v_and_or_b32 v3, v3, s6, v72
	v_lshl_add_u64 v[72:73], s[0:1], 1, v[68:69]
	v_readlane_b32 s0, v254, 31
	s_mul_hi_i32 s1, s41, s0
	s_mul_i32 s0, s41, s0
	v_readlane_b32 s6, v254, 32
	s_lshl_b64 s[0:1], s[0:1], 1
	s_mul_hi_i32 s25, s24, s6
	s_mul_i32 s24, s24, s6
	v_lshl_add_u64 v[140:141], v[72:73], 0, s[0:1]
	v_lshl_add_u64 v[72:73], s[24:25], 1, v[70:71]
	v_lshl_add_u64 v[142:143], v[72:73], 0, s[0:1]
	s_mul_hi_i32 s1, s22, s54
	s_mul_i32 s0, s22, s54
	v_lshrrev_b32_e32 v75, 4, v74
	v_bfe_u32 v76, v74, 4, 2
	v_lshl_add_u64 v[144:145], s[0:1], 1, v[68:69]
	v_bfe_u32 v68, v74, 1, 3
	v_lshl_add_u64 v[146:147], v[70:71], 0, s[26:27]
	v_bitop3_b32 v69, v75, v68, 3 bitop3:0x6c
	v_lshlrev_b32_e32 v70, 6, v74
	v_lshlrev_b32_e32 v71, 7, v74
	v_bitop3_b32 v68, v76, v68, 4 bitop3:0x36
	v_lshlrev_b32_e32 v69, 4, v69
	v_and_b32_e32 v70, 0xffffe000, v70
	v_and_b32_e32 v72, 0x780, v71
	v_and_b32_e32 v71, 0x2000, v71
	v_lshlrev_b32_e32 v68, 4, v68
	v_or_b32_e32 v73, v69, v70
	v_or_b32_e32 v69, v69, v71
	v_or_b32_e32 v70, v68, v70
	v_or_b32_e32 v68, v68, v71
	s_mov_b32 s42, 0
	v_add_u32_e32 v137, v73, v72
	v_add_u32_e32 v192, v69, v72
	v_add_u32_e32 v193, v70, v72
	v_add_u32_e32 v214, v68, v72
	s_mov_b32 s43, s40
	s_mov_b32 s44, 0
	s_mov_b32 s45, 0
	s_bfe_u32 vcc_lo, s101, 0x10001
	v_and_b32_e32 v20, 15, v194
	v_lshrrev_b32_e32 v21, 1, v20
	v_bfe_u32 v22, v194, 4, 2
	v_xor_b32_e32 v21, v21, v22
	v_lshlrev_b32_e32 v21, 4, v21
	v_lshl_or_b32 v250, v20, 7, v21
	v_mov_b32_e32 v22, vcc_lo
	v_lshl_or_b32 v22, v22, 13, v250
	v_or_b32_e32 v251, 0x4000, v22
	v_and_b32_e32 v20, 63, v194
	v_mov_b32_e32 v21, vcc_lo
	v_lshlrev_b32_e32 v21, 4, v21
	v_lshrrev_b32_e32 v22, 3, v20
	v_add_u32_e32 v21, v21, v22
	v_lshrrev_b32_e32 v22, 4, v20
	v_and_b32_e32 v23, 7, v20
	v_xor_b32_e32 v24, v23, v22
	v_lshlrev_b32_e32 v24, 4, v24
	v_or_b32_e32 v22, 4, v22
	v_xor_b32_e32 v25, v23, v22
	v_lshlrev_b32_e32 v25, 4, v25
	s_movk_i32 s98, 0x800
	s_movk_i32 s99, 0x800
	v_add_u32_e32 v26, 0, v21
	v_mad_u32_u24 v4, v26, s98, v24
	v_add_u32_e32 v26, 8, v21
	v_mad_u32_u24 v5, v26, s98, v25
	v_add_u32_e32 v26, 32, v21
	v_mad_u32_u24 v6, v26, s98, v24
	v_add_u32_e32 v26, 40, v21
	v_mad_u32_u24 v7, v26, s98, v25
	v_add_u32_e32 v26, 64, v21
	v_mad_u32_u24 v8, v26, s98, v24
	v_add_u32_e32 v26, 72, v21
	v_mad_u32_u24 v9, v26, s98, v25
	v_add_u32_e32 v26, 96, v21
	v_mad_u32_u24 v10, v26, s98, v24
	v_add_u32_e32 v26, 104, v21
	v_mad_u32_u24 v11, v26, s98, v25
	v_add_u32_e32 v26, 0, v21
	v_mad_u32_u24 v12, v26, s99, v24
	v_add_u32_e32 v26, 8, v21
	v_mad_u32_u24 v13, v26, s99, v25
	v_add_u32_e32 v26, 32, v21
	v_mad_u32_u24 v14, v26, s99, v24
	v_add_u32_e32 v26, 40, v21
	v_mad_u32_u24 v15, v26, s99, v25
	v_add_u32_e32 v26, 64, v21
	v_mad_u32_u24 v16, v26, s99, v24
	v_add_u32_e32 v26, 72, v21
	v_mad_u32_u24 v17, v26, s99, v25
	v_add_u32_e32 v26, 96, v21
	v_mad_u32_u24 v18, v26, s99, v24
	v_add_u32_e32 v26, 104, v21
	v_mad_u32_u24 v19, v26, s99, v25
	s_bfe_u32 vcc_hi, s101, 0x20002
	s_lshl_b32 vcc_hi, vcc_hi, 3
	s_mul_i32 s98, s98, vcc_hi
	s_mul_i32 s99, s99, vcc_hi
	s_lshl_b32 vcc_hi, vcc_hi, 3
	s_and_b32 vcc_hi, vcc_hi, 0x70
	s_add_u32 s98, s98, vcc_hi
	s_add_u32 s99, s99, vcc_hi
	s_lshl_b32 s100, vcc_lo, 11
	s_bitcmp1_b32 s101, 0
	s_cselect_b32 s100, -1, s100
	s_waitcnt vmcnt(0) lgkmcnt(0)
	s_barrier
	s_branch .LBB0_249

.Lmg_tf_0:
	s_cmp_lt_u32 s99, 0x440
	s_cselect_b32 s17, 1, 0
	s_lshr_b32 vcc_lo, s99, 6
	s_lshl_b32 vcc_lo, vcc_lo, 3
	s_and_b32 vcc_hi, s99, 7
	s_add_u32 vcc_lo, vcc_lo, vcc_hi
	s_lshl_b32 s10, vcc_lo, 7
	s_and_b32 vcc_hi, s99, 31
	s_or_b32 s10, s10, vcc_hi
	s_bfe_u32 vcc_lo, s99, 0x30003
	s_lshl_b32 s11, vcc_lo, 7
	s_cmp_eq_u32 s17, 0
	s_cbranch_scc1 .Lmg_exit
	s_mov_b32 s15, 1
	s_and_b32 s99, s34, 7
	s_lshl_b32 vcc_lo, s15, 3
	s_add_u32 s99, s99, vcc_lo
	s_mul_i32 s99, s99, s16
	s_lshr_b32 vcc_lo, s34, 3
	s_add_u32 s99, s99, vcc_lo
	s_sub_u32 vcc_lo, s99, 0x400
	s_cmp_lt_u32 vcc_lo, 0x200
	s_cbranch_scc0 .Lmg_tf_1
	s_bfe_u32 s99, s101, 0x80010
	s_add_u32 s99, s99, 0x400
	s_bitcmp1_b32 s101, 24
	s_cselect_b32 s99, s99, 0x7fff
.Lmg_tf_1:
	s_cmp_lt_u32 s99, 0x440
	s_cselect_b32 s17, 1, 0
	s_lshr_b32 vcc_lo, s99, 6
	s_lshl_b32 vcc_lo, vcc_lo, 3
	s_and_b32 vcc_hi, s99, 7
	s_add_u32 vcc_lo, vcc_lo, vcc_hi
	s_lshl_b32 s12, vcc_lo, 7
	s_and_b32 vcc_hi, s99, 31
	s_or_b32 s12, s12, vcc_hi
	s_bfe_u32 vcc_lo, s99, 0x30003
	s_lshl_b32 s13, vcc_lo, 7
	s_mov_b32 s14, 0
	s_bfe_u32 m0, s10, 0x20000
	s_add_u32 m0, m0, s14
	s_and_b32 m0, m0, 3
	s_andn2_b32 vcc_lo, s10, 0x7f
	s_lshl_b32 vcc_lo, vcc_lo, 12
	s_lshl_b32 vcc_hi, m0, 10
	s_add_u32 vcc_lo, vcc_lo, vcc_hi
	s_add_u32 s18, s0, vcc_lo
	s_addc_u32 s19, s1, 0
	s_lshl_b32 vcc_lo, s11, 10
	s_lshl_b32 vcc_hi, m0, 20
	s_add_u32 vcc_lo, vcc_lo, vcc_hi
	s_add_u32 s20, s2, vcc_lo
	s_addc_u32 s21, s3, 0
	s_bfe_u32 m0, s10, 0x20000
	s_add_u32 m0, m0, s14
	s_and_b32 m0, m0, 3
	s_andn2_b32 vcc_lo, s10, 0x7f
	s_lshl_b32 vcc_lo, vcc_lo, 13
	s_lshl_b32 vcc_hi, m0, 11
	s_add_u32 vcc_lo, vcc_lo, vcc_hi
	s_lshl_b32 vcc_hi, s11, 1
	s_add_u32 vcc_lo, vcc_lo, vcc_hi
	s_add_u32 s38, s6, vcc_lo
	s_addc_u32 s39, s7, 0
	s_andn2_b32 vcc_lo, s10, 0x7f
	s_lshl_b32 vcc_lo, vcc_lo, 11
	s_lshl_b32 vcc_hi, s11, 1
	s_add_u32 vcc_lo, vcc_lo, vcc_hi
	s_add_u32 s40, s8, vcc_lo
	s_addc_u32 s41, s9, 0
	s_cmp_lt_u32 s14, 3
	s_cbranch_scc0 .Lmg_nt_0
	s_add_u32 s99, s14, 1
	s_bfe_u32 m0, s10, 0x20000
	s_add_u32 m0, m0, s99
	s_and_b32 m0, m0, 3
	s_andn2_b32 vcc_lo, s10, 0x7f
	s_lshl_b32 vcc_lo, vcc_lo, 12
	s_lshl_b32 vcc_hi, m0, 10
	s_add_u32 vcc_lo, vcc_lo, vcc_hi
	s_add_u32 s22, s0, vcc_lo
	s_addc_u32 s23, s1, 0
	s_lshl_b32 vcc_lo, s11, 10
	s_lshl_b32 vcc_hi, m0, 20
	s_add_u32 vcc_lo, vcc_lo, vcc_hi
	s_add_u32 s24, s2, vcc_lo
	s_addc_u32 s25, s3, 0
	s_mov_b32 s35, 1
	s_branch .Lmg_nd_0
.Lmg_nt_0:
	s_mov_b32 s99, 0
	s_bfe_u32 m0, s12, 0x20000
	s_add_u32 m0, m0, s99
	s_and_b32 m0, m0, 3
	s_andn2_b32 vcc_lo, s12, 0x7f
	s_lshl_b32 vcc_lo, vcc_lo, 12
	s_lshl_b32 vcc_hi, m0, 10
	s_add_u32 vcc_lo, vcc_lo, vcc_hi
	s_add_u32 s22, s0, vcc_lo
	s_addc_u32 s23, s1, 0
	s_lshl_b32 vcc_lo, s13, 10
	s_lshl_b32 vcc_hi, m0, 20
	s_add_u32 vcc_lo, vcc_lo, vcc_hi
	s_add_u32 s24, s2, vcc_lo
	s_addc_u32 s25, s3, 0
	s_mov_b32 s35, s17
.Lmg_nd_0:
	s_mov_b32 vcc_lo, 0
	s_bfe_u32 vcc_hi, s10, 0x30002
	s_add_u32 vcc_lo, vcc_lo, vcc_hi
	s_and_b32 vcc_lo, vcc_lo, 7
	s_lshl_b32 vcc_lo, vcc_lo, 7
	s_add_u32 s26, s18, vcc_lo
	s_addc_u32 s27, s19, 0
	s_add_u32 s30, s20, vcc_lo
	s_addc_u32 s31, s21, 0
	s_add_u32 m0, s100, 0x0
	s_nop 0
	global_load_lds_dwordx4 v132, s[26:27]
	s_add_u32 m0, s100, 0x1000
	s_nop 0
	global_load_lds_dwordx4 v133, s[26:27]
	s_add_u32 m0, s100, 0x2000
	s_nop 0
	global_load_lds_dwordx4 v134, s[26:27]
	s_add_u32 m0, s100, 0x3000
	s_nop 0
	global_load_lds_dwordx4 v135, s[26:27]
	s_add_u32 m0, s100, 0x4000
	s_nop 0
	global_load_lds_dwordx4 v222, s[30:31]
	s_add_u32 m0, s100, 0x5000
	s_nop 0
	global_load_lds_dwordx4 v223, s[30:31]
	s_add_u32 m0, s100, 0x6000
	s_nop 0
	global_load_lds_dwordx4 v224, s[30:31]
	s_add_u32 m0, s100, 0x7000
	s_nop 0
	global_load_lds_dwordx4 v225, s[30:31]
	s_waitcnt vmcnt(0)
	s_barrier

.Lmg_body0:
	s_sub_u32 s99, s98, 1
	s_mov_b32 vcc_lo, s99
	s_bfe_u32 vcc_hi, s10, 0x30002
	s_add_u32 vcc_lo, vcc_lo, vcc_hi
	s_and_b32 vcc_lo, vcc_lo, 7
	s_lshl_b32 vcc_lo, vcc_lo, 7
	s_add_u32 s26, s18, vcc_lo
	s_addc_u32 s27, s19, 0
	s_add_u32 s30, s20, vcc_lo
	s_addc_u32 s31, s21, 0
	s_add_u32 m0, s100, 0x8000
	s_nop 0
	global_load_lds_dwordx4 v132, s[26:27]
	s_add_u32 m0, s100, 0x9000
	s_nop 0
	global_load_lds_dwordx4 v133, s[26:27]
	s_add_u32 m0, s100, 0xa000
	s_nop 0
	global_load_lds_dwordx4 v134, s[26:27]
	s_add_u32 m0, s100, 0xb000
	s_nop 0
	global_load_lds_dwordx4 v135, s[26:27]
	s_waitcnt lgkmcnt(7)
	ds_read_b128 v[172:175], v229
	ds_read_b128 v[176:179], v227
	ds_read_b128 v[180:183], v229 offset:2048
	ds_read_b128 v[184:187], v229 offset:4096
	ds_read_b128 v[188:191], v229 offset:6144
	ds_read_b128 v[208:211], v227 offset:2048
	ds_read_b128 v[214:217], v227 offset:4096
	ds_read_b128 v[218:221], v227 offset:6144
	s_add_u32 m0, s100, 0xc000
	s_waitcnt lgkmcnt(14)
	v_mfma_f32_16x16x32_bf16 v[68:71], v[140:143], v[144:147], v[68:71]
	global_load_lds_dwordx4 v222, s[30:31]
	s_waitcnt lgkmcnt(13)
	v_mfma_f32_16x16x32_bf16 v[72:75], v[148:151], v[144:147], v[72:75]
	s_waitcnt lgkmcnt(12)
	v_mfma_f32_16x16x32_bf16 v[76:79], v[152:155], v[144:147], v[76:79]
	s_waitcnt lgkmcnt(11)
	v_mfma_f32_16x16x32_bf16 v[80:83], v[156:159], v[144:147], v[80:83]
	s_add_u32 m0, s100, 0xd000
	s_waitcnt lgkmcnt(10)
	v_mfma_f32_16x16x32_bf16 v[84:87], v[140:143], v[160:163], v[84:87]
	global_load_lds_dwordx4 v223, s[30:31]
	v_mfma_f32_16x16x32_bf16 v[88:91], v[148:151], v[160:163], v[88:91]
	v_mfma_f32_16x16x32_bf16 v[92:95], v[152:155], v[160:163], v[92:95]
	v_mfma_f32_16x16x32_bf16 v[96:99], v[156:159], v[160:163], v[96:99]
	s_add_u32 m0, s100, 0xe000
	s_waitcnt lgkmcnt(9)
	v_mfma_f32_16x16x32_bf16 v[100:103], v[140:143], v[164:167], v[100:103]
	global_load_lds_dwordx4 v224, s[30:31]
	v_mfma_f32_16x16x32_bf16 v[104:107], v[148:151], v[164:167], v[104:107]
	v_mfma_f32_16x16x32_bf16 v[108:111], v[152:155], v[164:167], v[108:111]
	v_mfma_f32_16x16x32_bf16 v[112:115], v[156:159], v[164:167], v[112:115]
	s_add_u32 m0, s100, 0xf000
	s_waitcnt lgkmcnt(8)
	v_mfma_f32_16x16x32_bf16 v[116:119], v[140:143], v[168:171], v[116:119]
	global_load_lds_dwordx4 v225, s[30:31]
	v_mfma_f32_16x16x32_bf16 v[120:123], v[148:151], v[168:171], v[120:123]
	v_mfma_f32_16x16x32_bf16 v[124:127], v[152:155], v[168:171], v[124:127]
	v_mfma_f32_16x16x32_bf16 v[128:131], v[156:159], v[168:171], v[128:131]
	s_waitcnt lgkmcnt(6)
	v_mfma_f32_16x16x32_bf16 v[68:71], v[172:175], v[176:179], v[68:71]
	s_waitcnt lgkmcnt(5)
	v_mfma_f32_16x16x32_bf16 v[72:75], v[180:183], v[176:179], v[72:75]
	s_waitcnt lgkmcnt(4)
	v_mfma_f32_16x16x32_bf16 v[76:79], v[184:187], v[176:179], v[76:79]
	s_waitcnt lgkmcnt(3)
	v_mfma_f32_16x16x32_bf16 v[80:83], v[188:191], v[176:179], v[80:83]
	s_waitcnt lgkmcnt(2)
	v_mfma_f32_16x16x32_bf16 v[84:87], v[172:175], v[208:211], v[84:87]
	v_mfma_f32_16x16x32_bf16 v[88:91], v[180:183], v[208:211], v[88:91]
	v_mfma_f32_16x16x32_bf16 v[92:95], v[184:187], v[208:211], v[92:95]
	v_mfma_f32_16x16x32_bf16 v[96:99], v[188:191], v[208:211], v[96:99]
	s_cmp_lt_u32 s98, 8
	s_cbranch_scc1 .Lmg_samesub
	s_cmp_eq_u32 s35, 0
	s_cbranch_scc1 .Lmg_cur
	s_cmp_lt_u32 s14, 3
	s_cbranch_scc0 .Lmg_nxkey
	s_mov_b32 vcc_lo, 0
	s_bfe_u32 vcc_hi, s10, 0x30002
	s_add_u32 vcc_lo, vcc_lo, vcc_hi
	s_and_b32 vcc_lo, vcc_lo, 7
	s_lshl_b32 vcc_lo, vcc_lo, 7
	s_add_u32 s26, s22, vcc_lo
	s_addc_u32 s27, s23, 0
	s_add_u32 s30, s24, vcc_lo
	s_addc_u32 s31, s25, 0
	s_branch .Lmg_go
.Lmg_nxkey:
	s_mov_b32 vcc_lo, 0
	s_bfe_u32 vcc_hi, s12, 0x30002
	s_add_u32 vcc_lo, vcc_lo, vcc_hi
	s_and_b32 vcc_lo, vcc_lo, 7
	s_lshl_b32 vcc_lo, vcc_lo, 7
	s_add_u32 s26, s22, vcc_lo
	s_addc_u32 s27, s23, 0
	s_add_u32 s30, s24, vcc_lo
	s_addc_u32 s31, s25, 0
	s_branch .Lmg_go
.Lmg_cur:
	s_mov_b32 vcc_lo, 0
	s_bfe_u32 vcc_hi, s10, 0x30002
	s_add_u32 vcc_lo, vcc_lo, vcc_hi
	s_and_b32 vcc_lo, vcc_lo, 7
	s_lshl_b32 vcc_lo, vcc_lo, 7
	s_add_u32 s26, s18, vcc_lo
	s_addc_u32 s27, s19, 0
	s_add_u32 s30, s20, vcc_lo
	s_addc_u32 s31, s21, 0
	s_branch .Lmg_go
.Lmg_samesub:
	s_mov_b32 vcc_lo, s98
	s_bfe_u32 vcc_hi, s10, 0x30002
	s_add_u32 vcc_lo, vcc_lo, vcc_hi
	s_and_b32 vcc_lo, vcc_lo, 7
	s_lshl_b32 vcc_lo, vcc_lo, 7
	s_add_u32 s26, s18, vcc_lo
	s_addc_u32 s27, s19, 0
	s_add_u32 s30, s20, vcc_lo
	s_addc_u32 s31, s21, 0

.Lmg_tf_2:
	s_cmp_lt_u32 s99, 0x440
	s_cselect_b32 s17, 1, 0
	s_lshr_b32 vcc_lo, s99, 6
	s_lshl_b32 vcc_lo, vcc_lo, 3
	s_and_b32 vcc_hi, s99, 7
	s_add_u32 vcc_lo, vcc_lo, vcc_hi
	s_lshl_b32 s12, vcc_lo, 7
	s_and_b32 vcc_hi, s99, 31
	s_or_b32 s12, s12, vcc_hi
	s_bfe_u32 vcc_lo, s99, 0x30003
	s_lshl_b32 s13, vcc_lo, 7
	s_branch .Lmg_advd

.Lmg_advd:
	s_bfe_u32 m0, s10, 0x20000
	s_add_u32 m0, m0, s14
	s_and_b32 m0, m0, 3
	s_andn2_b32 vcc_lo, s10, 0x7f
	s_lshl_b32 vcc_lo, vcc_lo, 13
	s_lshl_b32 vcc_hi, m0, 11
	s_add_u32 vcc_lo, vcc_lo, vcc_hi
	s_lshl_b32 vcc_hi, s11, 1
	s_add_u32 vcc_lo, vcc_lo, vcc_hi
	s_add_u32 s38, s6, vcc_lo
	s_addc_u32 s39, s7, 0
	s_andn2_b32 vcc_lo, s10, 0x7f
	s_lshl_b32 vcc_lo, vcc_lo, 11
	s_lshl_b32 vcc_hi, s11, 1
	s_add_u32 vcc_lo, vcc_lo, vcc_hi
	s_add_u32 s40, s8, vcc_lo
	s_addc_u32 s41, s9, 0
	s_cmp_lt_u32 s14, 3
	s_cbranch_scc0 .Lmg_nt_1
	s_add_u32 s99, s14, 1
	s_bfe_u32 m0, s10, 0x20000
	s_add_u32 m0, m0, s99
	s_and_b32 m0, m0, 3
	s_andn2_b32 vcc_lo, s10, 0x7f
	s_lshl_b32 vcc_lo, vcc_lo, 12
	s_lshl_b32 vcc_hi, m0, 10
	s_add_u32 vcc_lo, vcc_lo, vcc_hi
	s_add_u32 s22, s0, vcc_lo
	s_addc_u32 s23, s1, 0
	s_lshl_b32 vcc_lo, s11, 10
	s_lshl_b32 vcc_hi, m0, 20
	s_add_u32 vcc_lo, vcc_lo, vcc_hi
	s_add_u32 s24, s2, vcc_lo
	s_addc_u32 s25, s3, 0
	s_mov_b32 s35, 1
	s_branch .Lmg_nd_1

.LBB0_295:
	s_or_b64 exec, exec, s[2:3]
	v_readlane_b32 s6, v253, 13
	s_waitcnt vmcnt(1)
	v_mov_b32_e32 v68, v194
	s_movk_i32 s0, 0x400
	s_movk_i32 s2, 0x400
	s_movk_i32 s1, 0x400
	v_readlane_b32 s7, v253, 14
	s_load_dword s3, s[6:7], 0x10
	s_load_dword s22, s[6:7], 0x0
	s_waitcnt lgkmcnt(0)
	s_lshr_b32 s3, s3, 16
	s_cmp_lg_u32 s3, 0
	s_cselect_b64 s[20:21], -1, 0
	s_cmp_lg_u64 s[20:21], 0
	s_addc_u32 s3, s22, 0
	s_lshr_b32 s46, s3, 3
	v_readlane_b32 s3, v254, 36
	s_mul_i32 s52, s46, s3
	v_readlane_b32 s3, v254, 30
	s_add_i32 s52, s52, s3
	s_cmpk_gt_i32 s52, 0x10ff
	s_cbranch_scc1 .LBB0_319
	v_readlane_b32 s6, v254, 63
	s_ashr_i32 s47, s1, 6
	v_readlane_b32 s7, v255, 0
	s_and_b64 s[20:21], s[6:7], exec
	s_mov_b32 s1, 0x2080000
	v_readlane_b32 s8, v252, 37
	s_cselect_b32 s1, s1, 0xc40000
	v_readlane_b32 s16, v252, 45
	v_readlane_b32 s17, v252, 46
	s_add_u32 s24, s16, s1
	s_addc_u32 s25, s17, 0
	s_ashr_i32 s1, s52, 31
	s_lshr_b32 s1, s1, 24
	v_readlane_b32 s20, v252, 49
	s_add_i32 s1, s52, s1
	s_ashr_i32 s1, s1, 8
	s_lshl_b32 s20, s52, 7
	v_lshlrev_b32_e32 v0, 3, v68
	v_readlane_b32 s21, v252, 50
	v_ashrrev_i32_e32 v3, 3, v68
	s_lshl_b32 s3, s1, 10
	s_and_b32 s20, s20, 0x380
	v_and_b32_e32 v0, 56, v0
	v_lshrrev_b32_e32 v132, 4, v68
	v_xor_b32_e32 v132, v132, v68
	v_and_b32_e32 v132, 7, v132
	v_lshlrev_b32_e32 v0, 3, v132
	v_mov_b32_e32 v1, v2
	s_or_b32 s55, s3, s20
	s_lshl_b32 s1, s1, 12
	s_lshl_b32 s3, s52, 4
	v_mad_i64_i32 v[4:5], s[20:21], s0, v3, v[0:1]
	v_mad_i64_i32 v[0:1], s[20:21], s2, v3, v[0:1]
	s_sub_i32 s1, s3, s1
	s_mul_hi_i32 s21, s55, s0
	s_mul_i32 s20, s55, s0
	s_and_b32 s53, s1, 0xffffff80
	s_ashr_i32 s1, s0, 31
	s_ashr_i32 s3, s2, 31
	s_lshl_b64 s[20:21], s[20:21], 1
	s_add_u32 s20, s76, s20
	s_addc_u32 s21, s77, s21
	v_lshlrev_b64 v[70:71], 1, v[4:5]
	v_lshl_add_u64 v[144:145], s[20:21], 0, v[70:71]
	s_mul_hi_i32 s21, s53, s2
	s_mul_i32 s20, s53, s2
	s_lshl_b64 s[20:21], s[20:21], 1
	s_add_u32 s20, s24, s20
	s_addc_u32 s21, s25, s21
	s_waitcnt vmcnt(0)
	v_lshlrev_b64 v[72:73], 1, v[0:1]
	v_readlane_b32 s22, v252, 51
	v_readlane_b32 s23, v252, 52
	v_lshl_add_u64 v[146:147], s[20:21], 0, v[72:73]
	s_lshl_b64 s[20:21], s[0:1], 6
	v_lshl_add_u64 v[0:1], v[144:145], 0, s[20:21]
	s_lshl_b64 s[22:23], s[2:3], 6
	s_waitcnt vmcnt(0)
	v_lshl_add_u64 v[36:37], v[0:1], 0, s[20:21]
	s_waitcnt vmcnt(0)
	v_lshl_add_u64 v[56:57], v[146:147], 0, s[22:23]
	v_lshl_add_u64 v[40:41], v[36:37], 0, s[20:21]
	s_waitcnt vmcnt(0)
	v_lshl_add_u64 v[60:61], v[56:57], 0, s[22:23]
	s_waitcnt vmcnt(0)
	v_lshl_add_u64 v[64:65], v[60:61], 0, s[22:23]
	s_bfe_u32 s100, s101, 0x20002
	s_lshl_b32 s100, s100, 10
	s_andn2_b32 s101, s101, 0x6000000
	s_bfe_u32 vcc_lo, s101, 0x80008
	s_add_u32 vcc_lo, vcc_lo, 0
	s_add_u32 vcc_hi, s47, -1
	s_and_b32 vcc_lo, vcc_lo, vcc_hi
	s_lshl_b32 vcc_lo, vcc_lo, 7
	s_mov_b32 vcc_hi, 0
	v_lshl_add_u64 v[20:21], v[144:145], 0, vcc
	s_add_u32 m0, s100, 0x0
	s_nop 0
	global_load_lds_dwordx4 v[20:21], off
	v_lshl_add_u64 v[20:21], v[0:1], 0, vcc
	s_add_u32 m0, s100, 0x1000
	s_nop 0
	global_load_lds_dwordx4 v[20:21], off
	v_lshl_add_u64 v[20:21], v[36:37], 0, vcc
	s_add_u32 m0, s100, 0x2000
	s_nop 0
	global_load_lds_dwordx4 v[20:21], off
	v_lshl_add_u64 v[20:21], v[40:41], 0, vcc
	s_add_u32 m0, s100, 0x3000
	s_nop 0
	global_load_lds_dwordx4 v[20:21], off
	v_lshl_add_u64 v[20:21], v[146:147], 0, vcc
	s_add_u32 m0, s100, 0x4000
	s_nop 0
	global_load_lds_dwordx4 v[20:21], off
	v_lshl_add_u64 v[20:21], v[56:57], 0, vcc
	s_add_u32 m0, s100, 0x5000
	s_nop 0
	global_load_lds_dwordx4 v[20:21], off
	v_lshl_add_u64 v[20:21], v[60:61], 0, vcc
	s_add_u32 m0, s100, 0x6000
	s_nop 0
	global_load_lds_dwordx4 v[20:21], off
	v_lshl_add_u64 v[20:21], v[64:65], 0, vcc
	s_add_u32 m0, s100, 0x7000
	s_nop 0
	global_load_lds_dwordx4 v[20:21], off
	s_bfe_u32 vcc_lo, s101, 0x80008
	s_add_u32 vcc_lo, vcc_lo, 1
	s_add_u32 vcc_hi, s47, -1
	s_and_b32 vcc_lo, vcc_lo, vcc_hi
	s_lshl_b32 vcc_lo, vcc_lo, 7
	s_mov_b32 vcc_hi, 0
	v_lshl_add_u64 v[20:21], v[144:145], 0, vcc
	s_add_u32 m0, s100, 0x8000
	s_nop 0
	global_load_lds_dwordx4 v[20:21], off
	v_lshl_add_u64 v[20:21], v[0:1], 0, vcc
	s_add_u32 m0, s100, 0x9000
	s_nop 0
	global_load_lds_dwordx4 v[20:21], off
	v_lshl_add_u64 v[20:21], v[36:37], 0, vcc
	s_add_u32 m0, s100, 0xa000
	s_nop 0
	global_load_lds_dwordx4 v[20:21], off
	v_lshl_add_u64 v[20:21], v[40:41], 0, vcc
	s_add_u32 m0, s100, 0xb000
	s_nop 0
	global_load_lds_dwordx4 v[20:21], off
	v_lshl_add_u64 v[20:21], v[146:147], 0, vcc
	s_add_u32 m0, s100, 0xc000
	s_nop 0
	global_load_lds_dwordx4 v[20:21], off
	v_lshl_add_u64 v[20:21], v[56:57], 0, vcc
	s_add_u32 m0, s100, 0xd000
	s_nop 0
	global_load_lds_dwordx4 v[20:21], off
	v_lshl_add_u64 v[20:21], v[60:61], 0, vcc
	s_add_u32 m0, s100, 0xe000
	s_nop 0
	global_load_lds_dwordx4 v[20:21], off
	v_lshl_add_u64 v[20:21], v[64:65], 0, vcc
	s_add_u32 m0, s100, 0xf000
	s_nop 0
	global_load_lds_dwordx4 v[20:21], off
	v_lshrrev_b32_e32 v1, 1, v3
	v_xor_b32_e32 v1, v1, v68
	v_lshlrev_b32_e32 v0, 7, v3
	v_lshlrev_b32_e32 v1, 4, v1
	s_movk_i32 s1, 0x70
	v_lshrrev_b32_e32 v69, 4, v68
	v_bfe_u32 v74, v68, 4, 2
	v_and_or_b32 v3, v1, s1, v0
	v_lshl_add_u64 v[0:1], s[76:77], 0, v[70:71]
	v_bfe_u32 v70, v68, 1, 3
	v_bitop3_b32 v69, v69, v70, 3 bitop3:0x6c
	v_lshlrev_b32_e32 v71, 6, v68
	v_lshlrev_b32_e32 v68, 7, v68
	v_bitop3_b32 v70, v74, v70, 4 bitop3:0x36
	v_lshl_add_u64 v[138:139], s[24:25], 0, v[72:73]
	v_lshlrev_b32_e32 v69, 4, v69
	v_and_b32_e32 v71, 0xffffe000, v71
	v_and_b32_e32 v72, 0x780, v68
	v_and_b32_e32 v68, 0x2000, v68
	v_lshlrev_b32_e32 v70, 4, v70
	s_cmp_gt_i32 s47, 0
	v_or_b32_e32 v73, v69, v71
	v_or_b32_e32 v69, v69, v68
	v_or_b32_e32 v71, v70, v71
	v_or_b32_e32 v68, v70, v68
	s_mov_b32 s49, 0
	s_cselect_b64 s[24:25], -1, 0
	v_add_u32_e32 v137, v73, v72
	v_add_u32_e32 v188, v69, v72
	v_add_u32_e32 v189, v71, v72
	v_add_u32_e32 v190, v68, v72
	s_mov_b32 s1, 0
	s_mov_b32 s3, 0
	v_readlane_b32 s9, v252, 38
	v_readlane_b32 s10, v252, 39
	v_readlane_b32 s11, v252, 40
	v_readlane_b32 s12, v252, 41
	v_readlane_b32 s13, v252, 42
	v_readlane_b32 s14, v252, 43
	v_readlane_b32 s15, v252, 44
	v_readlane_b32 s18, v252, 47
	v_readlane_b32 s19, v252, 48
	s_bfe_u32 vcc_lo, s101, 0x10001
	v_and_b32_e32 v20, 15, v194
	v_lshrrev_b32_e32 v21, 1, v20
	v_bfe_u32 v22, v194, 4, 2
	v_xor_b32_e32 v21, v21, v22
	v_lshlrev_b32_e32 v21, 4, v21
	v_lshl_or_b32 v250, v20, 7, v21
	v_mov_b32_e32 v22, vcc_lo
	v_lshl_or_b32 v22, v22, 13, v250
	v_or_b32_e32 v251, 0x4000, v22
	v_and_b32_e32 v20, 63, v194
	v_mov_b32_e32 v21, vcc_lo
	v_lshlrev_b32_e32 v21, 4, v21
	v_lshrrev_b32_e32 v22, 3, v20
	v_add_u32_e32 v21, v21, v22
	v_lshrrev_b32_e32 v22, 4, v20
	v_and_b32_e32 v23, 7, v20
	v_xor_b32_e32 v24, v23, v22
	v_lshlrev_b32_e32 v24, 4, v24
	v_or_b32_e32 v22, 4, v22
	v_xor_b32_e32 v25, v23, v22
	v_lshlrev_b32_e32 v25, 4, v25
	s_movk_i32 s98, 0x800
	s_movk_i32 s99, 0x800
	v_add_u32_e32 v26, 0, v21
	v_mad_u32_u24 v4, v26, s98, v24
	v_add_u32_e32 v26, 8, v21
	v_mad_u32_u24 v5, v26, s98, v25
	v_add_u32_e32 v26, 32, v21
	v_mad_u32_u24 v6, v26, s98, v24
	v_add_u32_e32 v26, 40, v21
	v_mad_u32_u24 v7, v26, s98, v25
	v_add_u32_e32 v26, 64, v21
	v_mad_u32_u24 v8, v26, s98, v24
	v_add_u32_e32 v26, 72, v21
	v_mad_u32_u24 v9, v26, s98, v25
	v_add_u32_e32 v26, 96, v21
	v_mad_u32_u24 v10, v26, s98, v24
	v_add_u32_e32 v26, 104, v21
	v_mad_u32_u24 v11, v26, s98, v25
	v_add_u32_e32 v26, 0, v21
	v_mad_u32_u24 v12, v26, s99, v24
	v_add_u32_e32 v26, 8, v21
	v_mad_u32_u24 v13, v26, s99, v25
	v_add_u32_e32 v26, 32, v21
	v_mad_u32_u24 v14, v26, s99, v24
	v_add_u32_e32 v26, 40, v21
	v_mad_u32_u24 v15, v26, s99, v25
	v_add_u32_e32 v26, 64, v21
	v_mad_u32_u24 v16, v26, s99, v24
	v_add_u32_e32 v26, 72, v21
	v_mad_u32_u24 v17, v26, s99, v25
	v_add_u32_e32 v26, 96, v21
	v_mad_u32_u24 v18, v26, s99, v24
	v_add_u32_e32 v26, 104, v21
	v_mad_u32_u24 v19, v26, s99, v25
	s_bfe_u32 vcc_hi, s101, 0x20002
	s_lshl_b32 vcc_hi, vcc_hi, 3
	s_mul_i32 s98, s98, vcc_hi
	s_mul_i32 s99, s99, vcc_hi
	s_lshl_b32 vcc_hi, vcc_hi, 3
	s_and_b32 vcc_hi, vcc_hi, 0x70
	s_add_u32 s98, s98, vcc_hi
	s_add_u32 s99, s99, vcc_hi
	s_lshl_b32 s100, vcc_lo, 11
	s_bitcmp1_b32 s101, 0
	s_cselect_b32 s100, -1, s100
	s_waitcnt vmcnt(0) lgkmcnt(0)
	s_barrier
	s_branch .LBB0_299

.LBB0_299:
	s_add_i32 s3, s3, 1
	s_lshl_b32 s26, s3, 3
	v_readlane_b32 s6, v254, 36
	s_or_b32 s26, s26, s6
	s_mul_i32 s34, s26, s46
	v_readlane_b32 s6, v254, 30
	s_add_i32 s34, s34, s6
	s_sub_u32 s26, s34, 0x1000
	s_cmp_lt_u32 s26, 0x200
	s_cbranch_scc0 .Ltailfix_1
	s_bfe_u32 s34, s101, 0x80010
	s_add_u32 s34, s34, 0x1000
	s_bitcmp1_b32 s101, 24
	s_cselect_b32 s34, s34, 0x7fff
	s_or_b32 s101, s101, 0x2000000

.Lpc_pgo_3:
	s_nop 0
	s_sub_u32 s40, s40, s98
	s_subb_u32 s41, s41, 0
	s_sub_u32 s38, s38, s99
	s_subb_u32 s39, s39, 0
	s_bfe_u32 vcc_hi, s101, 0x80008
	s_cmp_lt_i32 s96, s47
	s_cselect_b32 m0, 26, 25
	s_bitcmp1_b32 s101, m0
	s_cbranch_scc0 .Lpc_rt_3_0
	s_bfe_u32 vcc_hi, s101, 0x80010
.Lpc_rt_3_0:
	s_add_u32 vcc_hi, vcc_hi, vcc_lo
	s_add_u32 m0, s42, -1
	s_and_b32 vcc_hi, vcc_hi, m0
	s_lshl_b32 vcc_hi, vcc_hi, 7
	v_add_u32_e32 v20, vcc_hi, v4
	v_add_u32_e32 v21, vcc_hi, v5
	v_add_u32_e32 v22, vcc_hi, v6
	v_add_u32_e32 v23, vcc_hi, v7
	v_add_u32_e32 v24, vcc_hi, v8
	v_add_u32_e32 v25, vcc_hi, v9
	v_add_u32_e32 v26, vcc_hi, v10
	v_add_u32_e32 v27, vcc_hi, v11
	v_add_u32_e32 v28, vcc_hi, v12
	v_add_u32_e32 v29, vcc_hi, v13
	v_add_u32_e32 v30, vcc_hi, v14
	v_add_u32_e32 v31, vcc_hi, v15
	v_add_u32_e32 v32, vcc_hi, v16
	v_add_u32_e32 v33, vcc_hi, v17
	v_add_u32_e32 v34, vcc_hi, v18
	v_add_u32_e32 v35, vcc_hi, v19
	s_add_u32 vcc_lo, vcc_lo, 1
	s_barrier
	s_add_u32 m0, s100, 0x0
	s_nop 0
	global_load_lds_dwordx4 v20, s[40:41]
	s_add_u32 m0, s100, 0x400
	s_nop 0
	global_load_lds_dwordx4 v21, s[40:41]
	s_add_u32 m0, s100, 0x1000
	s_nop 0
	global_load_lds_dwordx4 v22, s[40:41]
	s_add_u32 m0, s100, 0x1400
	s_nop 0
	global_load_lds_dwordx4 v23, s[40:41]
	s_add_u32 m0, s100, 0x2000
	s_nop 0
	global_load_lds_dwordx4 v24, s[40:41]
	s_add_u32 m0, s100, 0x2400
	s_nop 0
	global_load_lds_dwordx4 v25, s[40:41]
	s_add_u32 m0, s100, 0x3000
	s_nop 0
	global_load_lds_dwordx4 v26, s[40:41]
	s_add_u32 m0, s100, 0x3400
	s_nop 0
	global_load_lds_dwordx4 v27, s[40:41]
	s_waitcnt vmcnt(8)
	s_barrier
	s_add_u32 m0, s100, 0x4000
	s_nop 0
	global_load_lds_dwordx4 v28, s[38:39]
	s_add_u32 m0, s100, 0x4400
	s_nop 0
	global_load_lds_dwordx4 v29, s[38:39]
	s_add_u32 m0, s100, 0x5000
	s_nop 0
	global_load_lds_dwordx4 v30, s[38:39]
	s_add_u32 m0, s100, 0x5400
	s_nop 0
	global_load_lds_dwordx4 v31, s[38:39]
	s_add_u32 m0, s100, 0x6000
	s_nop 0
	global_load_lds_dwordx4 v32, s[38:39]
	s_add_u32 m0, s100, 0x6400
	s_nop 0
	global_load_lds_dwordx4 v33, s[38:39]
	s_add_u32 m0, s100, 0x7000
	s_nop 0
	global_load_lds_dwordx4 v34, s[38:39]
	s_add_u32 m0, s100, 0x7400
	s_nop 0
	global_load_lds_dwordx4 v35, s[38:39]
	s_bfe_u32 vcc_hi, s101, 0x80008
	s_cmp_lt_i32 s96, s47
	s_cselect_b32 m0, 26, 25
	s_bitcmp1_b32 s101, m0
	s_cbranch_scc0 .Lpc_rt_3_1
	s_bfe_u32 vcc_hi, s101, 0x80010
.Lpc_rt_3_1:
	s_add_u32 vcc_hi, vcc_hi, vcc_lo
	s_add_u32 m0, s42, -1
	s_and_b32 vcc_hi, vcc_hi, m0
	s_lshl_b32 vcc_hi, vcc_hi, 7
	v_add_u32_e32 v20, vcc_hi, v4
	v_add_u32_e32 v21, vcc_hi, v5
	v_add_u32_e32 v22, vcc_hi, v6
	v_add_u32_e32 v23, vcc_hi, v7
	v_add_u32_e32 v24, vcc_hi, v8
	v_add_u32_e32 v25, vcc_hi, v9
	v_add_u32_e32 v26, vcc_hi, v10
	v_add_u32_e32 v27, vcc_hi, v11
	v_add_u32_e32 v28, vcc_hi, v12
	v_add_u32_e32 v29, vcc_hi, v13
	v_add_u32_e32 v30, vcc_hi, v14
	v_add_u32_e32 v31, vcc_hi, v15
	v_add_u32_e32 v32, vcc_hi, v16
	v_add_u32_e32 v33, vcc_hi, v17
	v_add_u32_e32 v34, vcc_hi, v18
	v_add_u32_e32 v35, vcc_hi, v19
	s_add_u32 vcc_lo, vcc_lo, 1
	s_barrier
	s_add_u32 m0, s100, 0x8000
	s_nop 0
	global_load_lds_dwordx4 v20, s[40:41]
	s_add_u32 m0, s100, 0x8400
	s_nop 0
	global_load_lds_dwordx4 v21, s[40:41]
	s_add_u32 m0, s100, 0x9000
	s_nop 0
	global_load_lds_dwordx4 v22, s[40:41]
	s_add_u32 m0, s100, 0x9400
	s_nop 0
	global_load_lds_dwordx4 v23, s[40:41]
	s_add_u32 m0, s100, 0xa000
	s_nop 0
	global_load_lds_dwordx4 v24, s[40:41]
	s_add_u32 m0, s100, 0xa400
	s_nop 0
	global_load_lds_dwordx4 v25, s[40:41]
	s_add_u32 m0, s100, 0xb000
	s_nop 0
	global_load_lds_dwordx4 v26, s[40:41]
	s_add_u32 m0, s100, 0xb400
	s_nop 0
	global_load_lds_dwordx4 v27, s[40:41]
	s_waitcnt vmcnt(8)
	s_barrier
	s_add_u32 m0, s100, 0xc000
	s_nop 0
	global_load_lds_dwordx4 v28, s[38:39]
	s_add_u32 m0, s100, 0xc400
	s_nop 0
	global_load_lds_dwordx4 v29, s[38:39]
	s_add_u32 m0, s100, 0xd000
	s_nop 0
	global_load_lds_dwordx4 v30, s[38:39]
	s_add_u32 m0, s100, 0xd400
	s_nop 0
	global_load_lds_dwordx4 v31, s[38:39]
	s_add_u32 m0, s100, 0xe000
	s_nop 0
	global_load_lds_dwordx4 v32, s[38:39]
	s_add_u32 m0, s100, 0xe400
	s_nop 0
	global_load_lds_dwordx4 v33, s[38:39]
	s_add_u32 m0, s100, 0xf000
	s_nop 0
	global_load_lds_dwordx4 v34, s[38:39]
	s_add_u32 m0, s100, 0xf400
	s_nop 0
	global_load_lds_dwordx4 v35, s[38:39]
	s_add_u32 s34, s34, 0x100
	s_addc_u32 s35, s35, 0
	s_add_i32 s96, s96, 2
	s_cmp_le_i32 s96, s47
	s_cbranch_scc1 .Lpc_ptop_3
	s_setprio 0
	s_bfe_u32 m0, s101, 0x10019
	s_andn2_b32 s101, s101, 0x6000000
	s_lshl_b32 m0, m0, 26
	s_or_b32 s101, s101, m0
	s_mov_b32 s97, s5
	s_movk_i32 s96, 0x43ff
	s_mov_b32 s55, s49
	s_mov_b32 s53, s1
	s_and_b64 vcc, exec, s[26:27]
	v_mov_b64_e32 v[146:147], v[142:143]
	v_mov_b64_e32 v[144:145], v[140:141]
	s_cbranch_vccz .Lpc_pnd_3
	s_waitcnt vmcnt(0)
	s_branch .LBB0_319

.LBB0_319:
	s_nop 0
	v_mov_b32_e32 v68, v194
	s_movk_i32 s0, 0x200
	s_movk_i32 s2, 0x200
	s_movk_i32 s1, 0x200
	s_cmpk_gt_i32 s52, 0x21f
	s_cbranch_scc1 .LBB0_342
	v_readlane_b32 s6, v254, 63
	s_ashr_i32 s47, s1, 6
	v_readlane_b32 s7, v255, 0
	s_and_b64 s[20:21], s[6:7], exec
	s_cselect_b32 s1, 0x80000, 0
	s_add_u32 s24, s74, s1
	s_addc_u32 s25, s75, 0
	s_ashr_i32 s1, s52, 31
	s_lshr_b32 s1, s1, 27
	s_add_i32 s1, s52, s1
	s_ashr_i32 s1, s1, 5
	s_lshl_b32 s20, s52, 7
	v_lshlrev_b32_e32 v0, 3, v68
	v_ashrrev_i32_e32 v3, 3, v68
	s_lshl_b32 s3, s1, 10
	s_and_b32 s20, s20, 0x380
	v_and_b32_e32 v0, 56, v0
	v_lshrrev_b32_e32 v132, 4, v68
	v_xor_b32_e32 v132, v132, v68
	v_and_b32_e32 v132, 7, v132
	v_lshlrev_b32_e32 v0, 3, v132
	v_mov_b32_e32 v1, v2
	s_or_b32 s53, s3, s20
	s_lshl_b32 s1, s1, 9
	s_lshl_b32 s3, s52, 4
	v_mad_i64_i32 v[4:5], s[20:21], s0, v3, v[0:1]
	v_mad_i64_i32 v[0:1], s[20:21], s2, v3, v[0:1]
	s_sub_i32 s1, s3, s1
	s_mul_hi_i32 s21, s0, s53
	s_mul_i32 s20, s0, s53
	s_and_b32 s52, s1, 0xffffff80
	s_ashr_i32 s1, s0, 31
	s_ashr_i32 s3, s2, 31
	s_lshl_b64 s[20:21], s[20:21], 1
	s_add_u32 s20, s82, s20
	s_addc_u32 s21, s83, s21
	v_lshlrev_b64 v[70:71], 1, v[4:5]
	v_lshl_add_u64 v[144:145], s[20:21], 0, v[70:71]
	s_mul_hi_i32 s21, s2, s52
	s_mul_i32 s20, s2, s52
	s_lshl_b64 s[20:21], s[20:21], 1
	s_add_u32 s20, s24, s20
	s_addc_u32 s21, s25, s21
	s_waitcnt vmcnt(0)
	v_lshlrev_b64 v[72:73], 1, v[0:1]
	v_lshl_add_u64 v[146:147], s[20:21], 0, v[72:73]
	s_lshl_b64 s[20:21], s[0:1], 6
	v_lshl_add_u64 v[0:1], v[144:145], 0, s[20:21]
	s_lshl_b64 s[22:23], s[2:3], 6
	s_waitcnt vmcnt(0)
	v_lshl_add_u64 v[36:37], v[0:1], 0, s[20:21]
	s_waitcnt vmcnt(0)
	v_lshl_add_u64 v[56:57], v[146:147], 0, s[22:23]
	v_lshl_add_u64 v[40:41], v[36:37], 0, s[20:21]
	s_waitcnt vmcnt(0)
	v_lshl_add_u64 v[60:61], v[56:57], 0, s[22:23]
	s_waitcnt vmcnt(0)
	v_lshl_add_u64 v[64:65], v[60:61], 0, s[22:23]
	s_bfe_u32 s100, s101, 0x20002
	s_lshl_b32 s100, s100, 10
	s_andn2_b32 s101, s101, 0x6000000
	s_bfe_u32 vcc_lo, s101, 0x80008
	s_add_u32 vcc_lo, vcc_lo, 0
	s_add_u32 vcc_hi, s47, -1
	s_and_b32 vcc_lo, vcc_lo, vcc_hi
	s_lshl_b32 vcc_lo, vcc_lo, 7
	s_mov_b32 vcc_hi, 0
	v_lshl_add_u64 v[20:21], v[144:145], 0, vcc
	s_add_u32 m0, s100, 0x0
	s_nop 0
	global_load_lds_dwordx4 v[20:21], off
	v_lshl_add_u64 v[20:21], v[0:1], 0, vcc
	s_add_u32 m0, s100, 0x1000
	s_nop 0
	global_load_lds_dwordx4 v[20:21], off
	v_lshl_add_u64 v[20:21], v[36:37], 0, vcc
	s_add_u32 m0, s100, 0x2000
	s_nop 0
	global_load_lds_dwordx4 v[20:21], off
	v_lshl_add_u64 v[20:21], v[40:41], 0, vcc
	s_add_u32 m0, s100, 0x3000
	s_nop 0
	global_load_lds_dwordx4 v[20:21], off
	v_lshl_add_u64 v[20:21], v[146:147], 0, vcc
	s_add_u32 m0, s100, 0x4000
	s_nop 0
	global_load_lds_dwordx4 v[20:21], off
	v_lshl_add_u64 v[20:21], v[56:57], 0, vcc
	s_add_u32 m0, s100, 0x5000
	s_nop 0
	global_load_lds_dwordx4 v[20:21], off
	v_lshl_add_u64 v[20:21], v[60:61], 0, vcc
	s_add_u32 m0, s100, 0x6000
	s_nop 0
	global_load_lds_dwordx4 v[20:21], off
	v_lshl_add_u64 v[20:21], v[64:65], 0, vcc
	s_add_u32 m0, s100, 0x7000
	s_nop 0
	global_load_lds_dwordx4 v[20:21], off
	s_bfe_u32 vcc_lo, s101, 0x80008
	s_add_u32 vcc_lo, vcc_lo, 1
	s_add_u32 vcc_hi, s47, -1
	s_and_b32 vcc_lo, vcc_lo, vcc_hi
	s_lshl_b32 vcc_lo, vcc_lo, 7
	s_mov_b32 vcc_hi, 0
	v_lshl_add_u64 v[20:21], v[144:145], 0, vcc
	s_add_u32 m0, s100, 0x8000
	s_nop 0
	global_load_lds_dwordx4 v[20:21], off
	v_lshl_add_u64 v[20:21], v[0:1], 0, vcc
	s_add_u32 m0, s100, 0x9000
	s_nop 0
	global_load_lds_dwordx4 v[20:21], off
	v_lshl_add_u64 v[20:21], v[36:37], 0, vcc
	s_add_u32 m0, s100, 0xa000
	s_nop 0
	global_load_lds_dwordx4 v[20:21], off
	v_lshl_add_u64 v[20:21], v[40:41], 0, vcc
	s_add_u32 m0, s100, 0xb000
	s_nop 0
	global_load_lds_dwordx4 v[20:21], off
	v_lshl_add_u64 v[20:21], v[146:147], 0, vcc
	s_add_u32 m0, s100, 0xc000
	s_nop 0
	global_load_lds_dwordx4 v[20:21], off
	v_lshl_add_u64 v[20:21], v[56:57], 0, vcc
	s_add_u32 m0, s100, 0xd000
	s_nop 0
	global_load_lds_dwordx4 v[20:21], off
	v_lshl_add_u64 v[20:21], v[60:61], 0, vcc
	s_add_u32 m0, s100, 0xe000
	s_nop 0
	global_load_lds_dwordx4 v[20:21], off
	v_lshl_add_u64 v[20:21], v[64:65], 0, vcc
	s_add_u32 m0, s100, 0xf000
	s_nop 0
	global_load_lds_dwordx4 v[20:21], off
	v_lshrrev_b32_e32 v1, 1, v3
	v_xor_b32_e32 v1, v1, v68
	v_lshlrev_b32_e32 v0, 7, v3
	v_lshlrev_b32_e32 v1, 4, v1
	s_movk_i32 s1, 0x70
	v_lshrrev_b32_e32 v69, 4, v68
	v_bfe_u32 v74, v68, 4, 2
	v_and_or_b32 v3, v1, s1, v0
	v_lshl_add_u64 v[0:1], s[82:83], 0, v[70:71]
	v_bfe_u32 v70, v68, 1, 3
	v_bitop3_b32 v69, v69, v70, 3 bitop3:0x6c
	v_lshlrev_b32_e32 v71, 6, v68
	v_lshlrev_b32_e32 v68, 7, v68
	v_bitop3_b32 v70, v74, v70, 4 bitop3:0x36
	v_lshl_add_u64 v[138:139], s[24:25], 0, v[72:73]
	v_lshlrev_b32_e32 v69, 4, v69
	v_and_b32_e32 v71, 0xffffe000, v71
	v_and_b32_e32 v72, 0x780, v68
	v_and_b32_e32 v68, 0x2000, v68
	v_lshlrev_b32_e32 v70, 4, v70
	s_cmp_gt_i32 s47, 0
	v_or_b32_e32 v73, v69, v71
	v_or_b32_e32 v69, v69, v68
	v_or_b32_e32 v71, v70, v71
	v_or_b32_e32 v68, v70, v68
	s_mov_b32 s49, 0
	s_cselect_b64 s[24:25], -1, 0
	v_add_u32_e32 v137, v73, v72
	v_add_u32_e32 v188, v69, v72
	v_add_u32_e32 v189, v71, v72
	v_add_u32_e32 v190, v68, v72
	s_mov_b32 s1, 0
	s_mov_b32 s3, 0
	s_bfe_u32 vcc_lo, s101, 0x10001
	v_and_b32_e32 v20, 15, v194
	v_lshrrev_b32_e32 v21, 1, v20
	v_bfe_u32 v22, v194, 4, 2
	v_xor_b32_e32 v21, v21, v22
	v_lshlrev_b32_e32 v21, 4, v21
	v_lshl_or_b32 v250, v20, 7, v21
	v_mov_b32_e32 v22, vcc_lo
	v_lshl_or_b32 v22, v22, 13, v250
	v_or_b32_e32 v251, 0x4000, v22
	v_and_b32_e32 v20, 63, v194
	v_mov_b32_e32 v21, vcc_lo
	v_lshlrev_b32_e32 v21, 4, v21
	v_lshrrev_b32_e32 v22, 3, v20
	v_add_u32_e32 v21, v21, v22
	v_lshrrev_b32_e32 v22, 4, v20
	v_and_b32_e32 v23, 7, v20
	v_xor_b32_e32 v24, v23, v22
	v_lshlrev_b32_e32 v24, 4, v24
	v_or_b32_e32 v22, 4, v22
	v_xor_b32_e32 v25, v23, v22
	v_lshlrev_b32_e32 v25, 4, v25
	s_movk_i32 s98, 0x400
	s_movk_i32 s99, 0x400
	v_add_u32_e32 v26, 0, v21
	v_mad_u32_u24 v4, v26, s98, v24
	v_add_u32_e32 v26, 8, v21
	v_mad_u32_u24 v5, v26, s98, v25
	v_add_u32_e32 v26, 32, v21
	v_mad_u32_u24 v6, v26, s98, v24
	v_add_u32_e32 v26, 40, v21
	v_mad_u32_u24 v7, v26, s98, v25
	v_add_u32_e32 v26, 64, v21
	v_mad_u32_u24 v8, v26, s98, v24
	v_add_u32_e32 v26, 72, v21
	v_mad_u32_u24 v9, v26, s98, v25
	v_add_u32_e32 v26, 96, v21
	v_mad_u32_u24 v10, v26, s98, v24
	v_add_u32_e32 v26, 104, v21
	v_mad_u32_u24 v11, v26, s98, v25
	v_add_u32_e32 v26, 0, v21
	v_mad_u32_u24 v12, v26, s99, v24
	v_add_u32_e32 v26, 8, v21
	v_mad_u32_u24 v13, v26, s99, v25
	v_add_u32_e32 v26, 32, v21
	v_mad_u32_u24 v14, v26, s99, v24
	v_add_u32_e32 v26, 40, v21
	v_mad_u32_u24 v15, v26, s99, v25
	v_add_u32_e32 v26, 64, v21
	v_mad_u32_u24 v16, v26, s99, v24
	v_add_u32_e32 v26, 72, v21
	v_mad_u32_u24 v17, v26, s99, v25
	v_add_u32_e32 v26, 96, v21
	v_mad_u32_u24 v18, v26, s99, v24
	v_add_u32_e32 v26, 104, v21
	v_mad_u32_u24 v19, v26, s99, v25
	s_bfe_u32 vcc_hi, s101, 0x20002
	s_lshl_b32 vcc_hi, vcc_hi, 3
	s_mul_i32 s98, s98, vcc_hi
	s_mul_i32 s99, s99, vcc_hi
	s_lshl_b32 vcc_hi, vcc_hi, 3
	s_and_b32 vcc_hi, vcc_hi, 0x70
	s_add_u32 s98, s98, vcc_hi
	s_add_u32 s99, s99, vcc_hi
	s_lshl_b32 s100, vcc_lo, 11
	s_bitcmp1_b32 s101, 0
	s_cselect_b32 s100, -1, s100
	s_waitcnt vmcnt(0) lgkmcnt(0)
	s_barrier
	s_branch .LBB0_323

.LBB0_323:
	s_add_i32 s3, s3, 1
	s_lshl_b32 s26, s3, 3
	v_readlane_b32 s5, v254, 36
	s_or_b32 s26, s26, s5
	s_mul_i32 s34, s26, s46
	v_readlane_b32 s5, v254, 30
	s_add_i32 s34, s34, s5
	s_sub_u32 s26, s34, 0x200
	s_cmp_lt_u32 s26, 0x200
	s_cbranch_scc0 .Ltailfix_2
	s_bfe_u32 s34, s101, 0x80010
	s_add_u32 s34, s34, 0x200
	s_bitcmp1_b32 s101, 24
	s_cselect_b32 s34, s34, 0x7fff
	s_or_b32 s101, s101, 0x2000000

.Lpc_rt_4_1:
	s_add_u32 vcc_hi, vcc_hi, vcc_lo
	s_add_u32 m0, s42, -1
	s_and_b32 vcc_hi, vcc_hi, m0
	s_lshl_b32 vcc_hi, vcc_hi, 7
	v_add_u32_e32 v20, vcc_hi, v4
	v_add_u32_e32 v21, vcc_hi, v5
	v_add_u32_e32 v22, vcc_hi, v6
	v_add_u32_e32 v23, vcc_hi, v7
	v_add_u32_e32 v24, vcc_hi, v8
	v_add_u32_e32 v25, vcc_hi, v9
	v_add_u32_e32 v26, vcc_hi, v10
	v_add_u32_e32 v27, vcc_hi, v11
	v_add_u32_e32 v28, vcc_hi, v12
	v_add_u32_e32 v29, vcc_hi, v13
	v_add_u32_e32 v30, vcc_hi, v14
	v_add_u32_e32 v31, vcc_hi, v15
	v_add_u32_e32 v32, vcc_hi, v16
	v_add_u32_e32 v33, vcc_hi, v17
	v_add_u32_e32 v34, vcc_hi, v18
	v_add_u32_e32 v35, vcc_hi, v19
	s_add_u32 vcc_lo, vcc_lo, 1
	s_barrier
	s_add_u32 m0, s100, 0x8000
	s_nop 0
	global_load_lds_dwordx4 v20, s[40:41]
	s_add_u32 m0, s100, 0x8400
	s_nop 0
	global_load_lds_dwordx4 v21, s[40:41]
	s_add_u32 m0, s100, 0x9000
	s_nop 0
	global_load_lds_dwordx4 v22, s[40:41]
	s_add_u32 m0, s100, 0x9400
	s_nop 0
	global_load_lds_dwordx4 v23, s[40:41]
	s_add_u32 m0, s100, 0xa000
	s_nop 0
	global_load_lds_dwordx4 v24, s[40:41]
	s_add_u32 m0, s100, 0xa400
	s_nop 0
	global_load_lds_dwordx4 v25, s[40:41]
	s_add_u32 m0, s100, 0xb000
	s_nop 0
	global_load_lds_dwordx4 v26, s[40:41]
	s_add_u32 m0, s100, 0xb400
	s_nop 0
	global_load_lds_dwordx4 v27, s[40:41]
	s_waitcnt vmcnt(8)
	s_barrier
	s_add_u32 m0, s100, 0xc000
	s_nop 0
	global_load_lds_dwordx4 v28, s[38:39]
	s_add_u32 m0, s100, 0xc400
	s_nop 0
	global_load_lds_dwordx4 v29, s[38:39]
	s_add_u32 m0, s100, 0xd000
	s_nop 0
	global_load_lds_dwordx4 v30, s[38:39]
	s_add_u32 m0, s100, 0xd400
	s_nop 0
	global_load_lds_dwordx4 v31, s[38:39]
	s_add_u32 m0, s100, 0xe000
	s_nop 0
	global_load_lds_dwordx4 v32, s[38:39]
	s_add_u32 m0, s100, 0xe400
	s_nop 0
	global_load_lds_dwordx4 v33, s[38:39]
	s_add_u32 m0, s100, 0xf000
	s_nop 0
	global_load_lds_dwordx4 v34, s[38:39]
	s_add_u32 m0, s100, 0xf400
	s_nop 0
	global_load_lds_dwordx4 v35, s[38:39]
	s_add_u32 s34, s34, 0x100
	s_addc_u32 s35, s35, 0
	s_add_i32 s55, s55, 2
	s_cmp_le_i32 s55, s47
	s_cbranch_scc1 .Lpc_ptop_4
	s_setprio 0
	s_bfe_u32 m0, s101, 0x10019
	s_andn2_b32 s101, s101, 0x6000000
	s_lshl_b32 m0, m0, 26
	s_or_b32 s101, s101, m0
	s_mov_b32 s53, s49
	s_mov_b32 s52, s1
	v_mov_b64_e32 v[146:147], v[142:143]
	v_mov_b64_e32 v[144:145], v[140:141]
	s_and_b64 vcc, exec, s[26:27]
	s_cbranch_vccz .Lpc_pnd_4
	s_waitcnt vmcnt(0)
	s_branch .LBB0_342

.LBB0_940:
	s_andn2_b64 vcc, exec, s[0:1]
	s_cbranch_vccnz .LBB0_992
	v_readlane_b32 s0, v255, 2
	s_cmp_gt_i32 s0, 0
	s_mov_b64 s[0:1], -1
	s_cbranch_scc0 .LBB0_966
	v_readlane_b32 s4, v253, 13
	s_waitcnt vmcnt(1)
	v_mov_b32_e32 v68, v194
	s_movk_i32 s0, 0x400
	s_movk_i32 s2, 0x400
	s_movk_i32 s3, 0x400
	v_readlane_b32 s5, v253, 14
	s_load_dword s1, s[4:5], 0x0
	v_readlane_b32 s4, v254, 30
	s_waitcnt lgkmcnt(0)
	s_lshr_b32 s46, s1, 3
	v_readlane_b32 s1, v254, 36
	s_mul_i32 s1, s46, s1
	s_add_i32 s1, s1, s4
	s_cmpk_gt_i32 s1, 0x1a07
	s_cbranch_scc1 .LBB0_965
	v_readlane_b32 s4, v254, 63
	s_ashr_i32 s47, s3, 6
	v_readlane_b32 s5, v255, 0
	s_and_b64 s[20:21], s[4:5], exec
	v_readlane_b32 s4, v252, 37
	s_cselect_b32 s3, 0x1440000, 0
	v_readlane_b32 s12, v252, 45
	v_readlane_b32 s13, v252, 46
	s_add_u32 s24, s12, s3
	s_mul_hi_i32 s3, s1, 0x5397829d
	s_addc_u32 s25, s13, 0
	s_lshr_b32 s20, s3, 31
	s_ashr_i32 s3, s3, 7
	s_add_i32 s3, s3, s20
	s_mul_i32 s20, s3, 0xfffffe78
	s_add_i32 s20, s20, s1
	s_lshl_b32 s1, s1, 7
	v_lshlrev_b32_e32 v0, 3, v68
	v_ashrrev_i32_e32 v3, 3, v68
	s_lshl_b32 s3, s3, 10
	s_and_b32 s1, s1, 0x380
	v_and_b32_e32 v0, 56, v0
	v_lshrrev_b32_e32 v132, 4, v68
	v_xor_b32_e32 v132, v132, v68
	v_and_b32_e32 v132, 7, v132
	v_lshlrev_b32_e32 v0, 3, v132
	v_mov_b32_e32 v1, v2
	s_or_b32 s52, s3, s1
	s_lshl_b32 s1, s20, 4
	v_mad_i64_i32 v[4:5], s[20:21], s0, v3, v[0:1]
	v_mad_i64_i32 v[0:1], s[20:21], s2, v3, v[0:1]
	s_mul_hi_i32 s21, s52, s0
	s_mul_i32 s20, s52, s0
	s_and_b32 s49, s1, 0xffffff80
	s_ashr_i32 s1, s0, 31
	s_ashr_i32 s3, s2, 31
	s_lshl_b64 s[20:21], s[20:21], 1
	s_add_u32 s20, s76, s20
	s_addc_u32 s21, s77, s21
	v_lshlrev_b64 v[70:71], 1, v[4:5]
	v_lshl_add_u64 v[144:145], s[20:21], 0, v[70:71]
	s_mul_hi_i32 s21, s49, s2
	s_mul_i32 s20, s49, s2
	s_lshl_b64 s[20:21], s[20:21], 1
	s_add_u32 s20, s24, s20
	s_addc_u32 s21, s25, s21
	s_waitcnt vmcnt(0)
	v_lshlrev_b64 v[72:73], 1, v[0:1]
	v_lshl_add_u64 v[146:147], s[20:21], 0, v[72:73]
	s_lshl_b64 s[20:21], s[0:1], 6
	v_lshl_add_u64 v[0:1], v[144:145], 0, s[20:21]
	s_lshl_b64 s[22:23], s[2:3], 6
	v_lshl_add_u64 v[36:37], v[0:1], 0, s[20:21]
	v_lshl_add_u64 v[56:57], v[146:147], 0, s[22:23]
	v_lshl_add_u64 v[40:41], v[36:37], 0, s[20:21]
	v_lshl_add_u64 v[60:61], v[56:57], 0, s[22:23]
	v_lshl_add_u64 v[64:65], v[60:61], 0, s[22:23]
	s_bfe_u32 s100, s101, 0x20002
	s_lshl_b32 s100, s100, 10
	s_andn2_b32 s101, s101, 0x6000000
	s_bfe_u32 vcc_lo, s101, 0x80008
	s_add_u32 vcc_lo, vcc_lo, 0
	s_add_u32 vcc_hi, s47, -1
	s_and_b32 vcc_lo, vcc_lo, vcc_hi
	s_lshl_b32 vcc_lo, vcc_lo, 7
	s_mov_b32 vcc_hi, 0
	v_lshl_add_u64 v[20:21], v[144:145], 0, vcc
	s_add_u32 m0, s100, 0x0
	s_nop 0
	global_load_lds_dwordx4 v[20:21], off
	v_lshl_add_u64 v[20:21], v[0:1], 0, vcc
	s_add_u32 m0, s100, 0x1000
	s_nop 0
	global_load_lds_dwordx4 v[20:21], off
	v_lshl_add_u64 v[20:21], v[36:37], 0, vcc
	s_add_u32 m0, s100, 0x2000
	s_nop 0
	global_load_lds_dwordx4 v[20:21], off
	v_lshl_add_u64 v[20:21], v[40:41], 0, vcc
	s_add_u32 m0, s100, 0x3000
	s_nop 0
	global_load_lds_dwordx4 v[20:21], off
	v_lshl_add_u64 v[20:21], v[146:147], 0, vcc
	s_add_u32 m0, s100, 0x4000
	s_nop 0
	global_load_lds_dwordx4 v[20:21], off
	v_lshl_add_u64 v[20:21], v[56:57], 0, vcc
	s_add_u32 m0, s100, 0x5000
	s_nop 0
	global_load_lds_dwordx4 v[20:21], off
	v_lshl_add_u64 v[20:21], v[60:61], 0, vcc
	s_add_u32 m0, s100, 0x6000
	s_nop 0
	global_load_lds_dwordx4 v[20:21], off
	v_lshl_add_u64 v[20:21], v[64:65], 0, vcc
	s_add_u32 m0, s100, 0x7000
	s_nop 0
	global_load_lds_dwordx4 v[20:21], off
	s_bfe_u32 vcc_lo, s101, 0x80008
	s_add_u32 vcc_lo, vcc_lo, 1
	s_add_u32 vcc_hi, s47, -1
	s_and_b32 vcc_lo, vcc_lo, vcc_hi
	s_lshl_b32 vcc_lo, vcc_lo, 7
	s_mov_b32 vcc_hi, 0
	v_lshl_add_u64 v[20:21], v[144:145], 0, vcc
	s_add_u32 m0, s100, 0x8000
	s_nop 0
	global_load_lds_dwordx4 v[20:21], off
	v_lshl_add_u64 v[20:21], v[0:1], 0, vcc
	s_add_u32 m0, s100, 0x9000
	s_nop 0
	global_load_lds_dwordx4 v[20:21], off
	v_lshl_add_u64 v[20:21], v[36:37], 0, vcc
	s_add_u32 m0, s100, 0xa000
	s_nop 0
	global_load_lds_dwordx4 v[20:21], off
	v_lshl_add_u64 v[20:21], v[40:41], 0, vcc
	s_add_u32 m0, s100, 0xb000
	s_nop 0
	global_load_lds_dwordx4 v[20:21], off
	v_lshl_add_u64 v[20:21], v[146:147], 0, vcc
	s_add_u32 m0, s100, 0xc000
	s_nop 0
	global_load_lds_dwordx4 v[20:21], off
	v_lshl_add_u64 v[20:21], v[56:57], 0, vcc
	s_add_u32 m0, s100, 0xd000
	s_nop 0
	global_load_lds_dwordx4 v[20:21], off
	v_lshl_add_u64 v[20:21], v[60:61], 0, vcc
	s_add_u32 m0, s100, 0xe000
	s_nop 0
	global_load_lds_dwordx4 v[20:21], off
	v_lshl_add_u64 v[20:21], v[64:65], 0, vcc
	s_add_u32 m0, s100, 0xf000
	s_nop 0
	global_load_lds_dwordx4 v[20:21], off
	v_lshrrev_b32_e32 v1, 1, v3
	v_xor_b32_e32 v1, v1, v68
	v_lshlrev_b32_e32 v0, 7, v3
	v_lshlrev_b32_e32 v1, 4, v1
	s_movk_i32 s1, 0x70
	v_lshrrev_b32_e32 v69, 4, v68
	v_bfe_u32 v74, v68, 4, 2
	v_and_or_b32 v3, v1, s1, v0
	v_lshl_add_u64 v[0:1], s[76:77], 0, v[70:71]
	v_bfe_u32 v70, v68, 1, 3
	v_bitop3_b32 v69, v69, v70, 3 bitop3:0x6c
	v_lshlrev_b32_e32 v71, 6, v68
	v_lshlrev_b32_e32 v68, 7, v68
	v_bitop3_b32 v70, v74, v70, 4 bitop3:0x36
	v_lshl_add_u64 v[138:139], s[24:25], 0, v[72:73]
	v_lshlrev_b32_e32 v69, 4, v69
	v_and_b32_e32 v71, 0xffffe000, v71
	v_and_b32_e32 v72, 0x780, v68
	v_and_b32_e32 v68, 0x2000, v68
	v_lshlrev_b32_e32 v70, 4, v70
	s_cmp_gt_i32 s47, 0
	v_or_b32_e32 v73, v69, v71
	v_or_b32_e32 v69, v69, v68
	v_or_b32_e32 v71, v70, v71
	v_or_b32_e32 v68, v70, v68
	s_mov_b32 s48, 0
	s_cselect_b64 s[24:25], -1, 0
	v_add_u32_e32 v137, v73, v72
	v_add_u32_e32 v188, v69, v72
	v_add_u32_e32 v189, v71, v72
	v_add_u32_e32 v190, v68, v72
	s_mov_b32 s1, 0
	s_mov_b32 s3, 0
	v_readlane_b32 s5, v252, 38
	v_readlane_b32 s6, v252, 39
	v_readlane_b32 s7, v252, 40
	v_readlane_b32 s8, v252, 41
	v_readlane_b32 s9, v252, 42
	v_readlane_b32 s10, v252, 43
	v_readlane_b32 s11, v252, 44
	v_readlane_b32 s14, v252, 47
	v_readlane_b32 s15, v252, 48
	v_readlane_b32 s16, v252, 49
	v_readlane_b32 s17, v252, 50
	v_readlane_b32 s18, v252, 51
	v_readlane_b32 s19, v252, 52
	s_bfe_u32 vcc_lo, s101, 0x10001
	v_and_b32_e32 v20, 15, v194
	v_lshrrev_b32_e32 v21, 1, v20
	v_bfe_u32 v22, v194, 4, 2
	v_xor_b32_e32 v21, v21, v22
	v_lshlrev_b32_e32 v21, 4, v21
	v_lshl_or_b32 v250, v20, 7, v21
	v_mov_b32_e32 v22, vcc_lo
	v_lshl_or_b32 v22, v22, 13, v250
	v_or_b32_e32 v251, 0x4000, v22
	v_and_b32_e32 v20, 63, v194
	v_mov_b32_e32 v21, vcc_lo
	v_lshlrev_b32_e32 v21, 4, v21
	v_lshrrev_b32_e32 v22, 3, v20
	v_add_u32_e32 v21, v21, v22
	v_lshrrev_b32_e32 v22, 4, v20
	v_and_b32_e32 v23, 7, v20
	v_xor_b32_e32 v24, v23, v22
	v_lshlrev_b32_e32 v24, 4, v24
	v_or_b32_e32 v22, 4, v22
	v_xor_b32_e32 v25, v23, v22
	v_lshlrev_b32_e32 v25, 4, v25
	s_movk_i32 s98, 0x800
	s_movk_i32 s99, 0x800
	v_add_u32_e32 v26, 0, v21
	v_mad_u32_u24 v4, v26, s98, v24
	v_add_u32_e32 v26, 8, v21
	v_mad_u32_u24 v5, v26, s98, v25
	v_add_u32_e32 v26, 32, v21
	v_mad_u32_u24 v6, v26, s98, v24
	v_add_u32_e32 v26, 40, v21
	v_mad_u32_u24 v7, v26, s98, v25
	v_add_u32_e32 v26, 64, v21
	v_mad_u32_u24 v8, v26, s98, v24
	v_add_u32_e32 v26, 72, v21
	v_mad_u32_u24 v9, v26, s98, v25
	v_add_u32_e32 v26, 96, v21
	v_mad_u32_u24 v10, v26, s98, v24
	v_add_u32_e32 v26, 104, v21
	v_mad_u32_u24 v11, v26, s98, v25
	v_add_u32_e32 v26, 0, v21
	v_mad_u32_u24 v12, v26, s99, v24
	v_add_u32_e32 v26, 8, v21
	v_mad_u32_u24 v13, v26, s99, v25
	v_add_u32_e32 v26, 32, v21
	v_mad_u32_u24 v14, v26, s99, v24
	v_add_u32_e32 v26, 40, v21
	v_mad_u32_u24 v15, v26, s99, v25
	v_add_u32_e32 v26, 64, v21
	v_mad_u32_u24 v16, v26, s99, v24
	v_add_u32_e32 v26, 72, v21
	v_mad_u32_u24 v17, v26, s99, v25
	v_add_u32_e32 v26, 96, v21
	v_mad_u32_u24 v18, v26, s99, v24
	v_add_u32_e32 v26, 104, v21
	v_mad_u32_u24 v19, v26, s99, v25
	s_bfe_u32 vcc_hi, s101, 0x20002
	s_lshl_b32 vcc_hi, vcc_hi, 3
	s_mul_i32 s98, s98, vcc_hi
	s_mul_i32 s99, s99, vcc_hi
	s_lshl_b32 vcc_hi, vcc_hi, 3
	s_and_b32 vcc_hi, vcc_hi, 0x70
	s_add_u32 s98, s98, vcc_hi
	s_add_u32 s99, s99, vcc_hi
	s_lshl_b32 s100, vcc_lo, 11
	s_bitcmp1_b32 s101, 0
	s_cselect_b32 s100, -1, s100
	s_waitcnt vmcnt(0) lgkmcnt(0)
	s_barrier
	s_branch .LBB0_946

.LBB0_946:
	s_add_i32 s3, s3, 1
	s_lshl_b32 s26, s3, 3
	v_readlane_b32 s4, v254, 36
	s_or_b32 s26, s26, s4
	s_mul_i32 s34, s26, s46
	v_readlane_b32 s4, v254, 30
	s_add_i32 s34, s34, s4
	s_sub_u32 s26, s34, 0x1a00
	s_cmp_lt_u32 s26, 0x200
	s_cbranch_scc0 .Ltailfix_3
	s_bfe_u32 s34, s101, 0x80010
	s_add_u32 s34, s34, 0x1a00
	s_bitcmp1_b32 s101, 24
	s_cselect_b32 s34, s34, 0x7fff
	s_or_b32 s101, s101, 0x2000000

.Lpc_pgo_1:
	s_nop 0
	s_sub_u32 s40, s40, s98
	s_subb_u32 s41, s41, 0
	s_sub_u32 s38, s38, s99
	s_subb_u32 s39, s39, 0
	s_bfe_u32 vcc_hi, s101, 0x80008
	s_cmp_lt_i32 s53, s47
	s_cselect_b32 m0, 26, 25
	s_bitcmp1_b32 s101, m0
	s_cbranch_scc0 .Lpc_rt_1_0
	s_bfe_u32 vcc_hi, s101, 0x80010
.Lpc_rt_1_0:
	s_add_u32 vcc_hi, vcc_hi, vcc_lo
	s_add_u32 m0, s42, -1
	s_and_b32 vcc_hi, vcc_hi, m0
	s_lshl_b32 vcc_hi, vcc_hi, 7
	v_add_u32_e32 v20, vcc_hi, v4
	v_add_u32_e32 v21, vcc_hi, v5
	v_add_u32_e32 v22, vcc_hi, v6
	v_add_u32_e32 v23, vcc_hi, v7
	v_add_u32_e32 v24, vcc_hi, v8
	v_add_u32_e32 v25, vcc_hi, v9
	v_add_u32_e32 v26, vcc_hi, v10
	v_add_u32_e32 v27, vcc_hi, v11
	v_add_u32_e32 v28, vcc_hi, v12
	v_add_u32_e32 v29, vcc_hi, v13
	v_add_u32_e32 v30, vcc_hi, v14
	v_add_u32_e32 v31, vcc_hi, v15
	v_add_u32_e32 v32, vcc_hi, v16
	v_add_u32_e32 v33, vcc_hi, v17
	v_add_u32_e32 v34, vcc_hi, v18
	v_add_u32_e32 v35, vcc_hi, v19
	s_add_u32 vcc_lo, vcc_lo, 1
	s_barrier
	s_add_u32 m0, s100, 0x0
	s_nop 0
	global_load_lds_dwordx4 v20, s[40:41]
	s_add_u32 m0, s100, 0x400
	s_nop 0
	global_load_lds_dwordx4 v21, s[40:41]
	s_add_u32 m0, s100, 0x1000
	s_nop 0
	global_load_lds_dwordx4 v22, s[40:41]
	s_add_u32 m0, s100, 0x1400
	s_nop 0
	global_load_lds_dwordx4 v23, s[40:41]
	s_add_u32 m0, s100, 0x2000
	s_nop 0
	global_load_lds_dwordx4 v24, s[40:41]
	s_add_u32 m0, s100, 0x2400
	s_nop 0
	global_load_lds_dwordx4 v25, s[40:41]
	s_add_u32 m0, s100, 0x3000
	s_nop 0
	global_load_lds_dwordx4 v26, s[40:41]
	s_add_u32 m0, s100, 0x3400
	s_nop 0
	global_load_lds_dwordx4 v27, s[40:41]
	s_waitcnt vmcnt(8)
	s_barrier
	s_add_u32 m0, s100, 0x4000
	s_nop 0
	global_load_lds_dwordx4 v28, s[38:39]
	s_add_u32 m0, s100, 0x4400
	s_nop 0
	global_load_lds_dwordx4 v29, s[38:39]
	s_add_u32 m0, s100, 0x5000
	s_nop 0
	global_load_lds_dwordx4 v30, s[38:39]
	s_add_u32 m0, s100, 0x5400
	s_nop 0
	global_load_lds_dwordx4 v31, s[38:39]
	s_add_u32 m0, s100, 0x6000
	s_nop 0
	global_load_lds_dwordx4 v32, s[38:39]
	s_add_u32 m0, s100, 0x6400
	s_nop 0
	global_load_lds_dwordx4 v33, s[38:39]
	s_add_u32 m0, s100, 0x7000
	s_nop 0
	global_load_lds_dwordx4 v34, s[38:39]
	s_add_u32 m0, s100, 0x7400
	s_nop 0
	global_load_lds_dwordx4 v35, s[38:39]
	s_bfe_u32 vcc_hi, s101, 0x80008
	s_cmp_lt_i32 s53, s47
	s_cselect_b32 m0, 26, 25
	s_bitcmp1_b32 s101, m0
	s_cbranch_scc0 .Lpc_rt_1_1
	s_bfe_u32 vcc_hi, s101, 0x80010
.Lpc_rt_1_1:
	s_add_u32 vcc_hi, vcc_hi, vcc_lo
	s_add_u32 m0, s42, -1
	s_and_b32 vcc_hi, vcc_hi, m0
	s_lshl_b32 vcc_hi, vcc_hi, 7
	v_add_u32_e32 v20, vcc_hi, v4
	v_add_u32_e32 v21, vcc_hi, v5
	v_add_u32_e32 v22, vcc_hi, v6
	v_add_u32_e32 v23, vcc_hi, v7
	v_add_u32_e32 v24, vcc_hi, v8
	v_add_u32_e32 v25, vcc_hi, v9
	v_add_u32_e32 v26, vcc_hi, v10
	v_add_u32_e32 v27, vcc_hi, v11
	v_add_u32_e32 v28, vcc_hi, v12
	v_add_u32_e32 v29, vcc_hi, v13
	v_add_u32_e32 v30, vcc_hi, v14
	v_add_u32_e32 v31, vcc_hi, v15
	v_add_u32_e32 v32, vcc_hi, v16
	v_add_u32_e32 v33, vcc_hi, v17
	v_add_u32_e32 v34, vcc_hi, v18
	v_add_u32_e32 v35, vcc_hi, v19
	s_add_u32 vcc_lo, vcc_lo, 1
	s_barrier
	s_add_u32 m0, s100, 0x8000
	s_nop 0
	global_load_lds_dwordx4 v20, s[40:41]
	s_add_u32 m0, s100, 0x8400
	s_nop 0
	global_load_lds_dwordx4 v21, s[40:41]
	s_add_u32 m0, s100, 0x9000
	s_nop 0
	global_load_lds_dwordx4 v22, s[40:41]
	s_add_u32 m0, s100, 0x9400
	s_nop 0
	global_load_lds_dwordx4 v23, s[40:41]
	s_add_u32 m0, s100, 0xa000
	s_nop 0
	global_load_lds_dwordx4 v24, s[40:41]
	s_add_u32 m0, s100, 0xa400
	s_nop 0
	global_load_lds_dwordx4 v25, s[40:41]
	s_add_u32 m0, s100, 0xb000
	s_nop 0
	global_load_lds_dwordx4 v26, s[40:41]
	s_add_u32 m0, s100, 0xb400
	s_nop 0
	global_load_lds_dwordx4 v27, s[40:41]
	s_waitcnt vmcnt(8)
	s_barrier
	s_add_u32 m0, s100, 0xc000
	s_nop 0
	global_load_lds_dwordx4 v28, s[38:39]
	s_add_u32 m0, s100, 0xc400
	s_nop 0
	global_load_lds_dwordx4 v29, s[38:39]
	s_add_u32 m0, s100, 0xd000
	s_nop 0
	global_load_lds_dwordx4 v30, s[38:39]
	s_add_u32 m0, s100, 0xd400
	s_nop 0
	global_load_lds_dwordx4 v31, s[38:39]
	s_add_u32 m0, s100, 0xe000
	s_nop 0
	global_load_lds_dwordx4 v32, s[38:39]
	s_add_u32 m0, s100, 0xe400
	s_nop 0
	global_load_lds_dwordx4 v33, s[38:39]
	s_add_u32 m0, s100, 0xf000
	s_nop 0
	global_load_lds_dwordx4 v34, s[38:39]
	s_add_u32 m0, s100, 0xf400
	s_nop 0
	global_load_lds_dwordx4 v35, s[38:39]
	s_add_u32 s34, s34, 0x100
	s_addc_u32 s35, s35, 0
	s_add_i32 s53, s53, 2
	s_cmp_le_i32 s53, s47
	s_cbranch_scc1 .Lpc_ptop_1
	s_setprio 0
	s_bfe_u32 m0, s101, 0x10019
	s_andn2_b32 s101, s101, 0x6000000
	s_lshl_b32 m0, m0, 26
	s_or_b32 s101, s101, m0
	s_movk_i32 s4, 0x3100
	s_mov_b32 s52, s48
	s_mov_b32 s49, s1
	s_and_b64 vcc, exec, s[26:27]
	v_mov_b64_e32 v[146:147], v[142:143]
	v_mov_b64_e32 v[144:145], v[140:141]
	s_cbranch_vccz .Lpc_pnd_1
	s_waitcnt vmcnt(0)
	s_branch .LBB0_965
